# P1/P5/P6 K-loops: LDS-DMA issues ahead of the ds_reads in every load segment
# baseline (speedup 1.0000x reference)
; #define PG8_STAGE(bufoff, gbase, voff) do { _Pragma("unroll") for (int _i = 0; _i < 2; ++_i) \
;         __builtin_amdgcn_global_load_lds((const unsigned*)((const char*)(gbase) + (voff)[_i]), (PG8_LAS unsigned*)(lds + (bufoff) + ldsw + _i * 8192), 16, 0, 0); } while (0)
; #define PG8_LDA(dst, b, h) do { _Pragma("unroll") for (int m = 0; m < 4; ++m) _Pragma("unroll") for (int k = 0; k < 2; ++k) dst[m][k] = *(const PG8_LAS bf16x8*)(lds + PG8_SA(b, h) + aoff + m * 2048 + k * 1024); } while (0)
; #define PG8_LDB(dst, b, h) do { _Pragma("unroll") for (int n = 0; n < 2; ++n) _Pragma("unroll") for (int k = 0; k < 2; ++k) dst[n][k] = *(const PG8_LAS bf16x8*)(lds + PG8_SB(b, h) + boff + n * 2048 + k * 1024); } while (0)
; #define PG8_MMA(ai, bj, At, Bt) do { __builtin_amdgcn_s_setprio(1); _Pragma("unroll") for (int m = 0; m < 4; ++m) _Pragma("unroll") for (int n = 0; n < 2; ++n) _Pragma("unroll") for (int k = 0; k < 2; ++k) \
;         acc[ai][bj][m][n] = __builtin_amdgcn_mfma_f32_16x16x32_bf16(Bt[n][k], At[m][k], acc[ai][bj][m][n], 0, 0, 0); __builtin_amdgcn_s_setprio(0); } while (0)
; #define PG8_WAIT_V(n) asm volatile("s_waitcnt vmcnt(" #n ")" ::: "memory")
; #define PG8_WAIT_L(n) asm volatile("s_waitcnt lgkmcnt(" #n ")" ::: "memory")
; #define PG8_BAR __builtin_amdgcn_s_barrier()
; #define PG8_SCHED __builtin_amdgcn_sched_barrier(0)
; template <class Epi, class Sched, bool ALIGN_EPI>
; __device__ __forceinline__ void gemm_phase(PG8_LAS unsigned char* lds, const Gemm g, const Sched& S, const Epi& E) {
;     ...
;             const char* a1 = cA + (size_t)(t + 1) * kstepA;
;             const char* a2 = last ? nA : cA + (size_t)(t + 2) * kstepA; const char* b2 = last ? nB : cB + (size_t)(t + 2) * kstep;
;             const char* a3 = a2 + kstepA; const char* b3 = b2 + kstep;
;             PG8_LDB(B0, 0, 0); PG8_LDB(B1, 0, 1); PG8_SCHED; PG8_LDA(At, 0, 0); PG8_STAGE(PG8_SA(1, 1), a1 + hstepA, voffA);
;             PG8_WAIT_V(8); PG8_WAIT_L(0); PG8_BAR; PG8_MMA(0, 0, At, B0); PG8_MMA(0, 1, At, B1); PG8_BAR; PG8_SCHED;
;             PG8_LDA(At, 0, 1); PG8_STAGE(PG8_SB(0, 0), b2, voffB); PG8_STAGE(PG8_SB(0, 1), b2 + hstepB, voffB); PG8_STAGE(PG8_SA(0, 0), a2, voffA);
;             PG8_WAIT_V(8); PG8_WAIT_L(0); PG8_BAR; PG8_MMA(1, 0, At, B0); PG8_MMA(1, 1, At, B1); PG8_BAR; PG8_SCHED;
.LBB0_403:
	s_add_u32 s23, s24, 0xfff80080
	s_addc_u32 s26, s25, -1
	s_cmp_eq_u32 s17, 28
	s_cselect_b32 s29, s19, s26
	s_cselect_b32 s28, s18, s23
	s_cselect_b32 s27, s21, s15
	s_cselect_b32 s26, s20, s5
	v_lshl_add_u64 v[156:157], s[24:25], 0, v[140:141]
	s_add_i32 m0, s34, 0xc000
	s_nop 0
	global_load_lds_dwordx4 v[156:157], off
	v_lshl_add_u64 v[156:157], s[24:25], 0, v[142:143]
	s_add_i32 m0, s34, 0xe000
	s_nop 0
	global_load_lds_dwordx4 v[156:157], off
	ds_read_b128 v[152:155], v166
	ds_read_b128 v[172:175], v166 offset:1024
	ds_read_b128 v[176:179], v166 offset:2048
	ds_read_b128 v[180:183], v166 offset:3072
	ds_read_b128 v[184:187], v167
	ds_read_b128 v[188:191], v167 offset:1024
	ds_read_b128 v[192:195], v167 offset:2048
	ds_read_b128 v[196:199], v167 offset:3072
	ds_read_b128 v[200:203], v168
	ds_read_b128 v[204:207], v168 offset:1024
	ds_read_b128 v[208:211], v168 offset:2048
	ds_read_b128 v[212:215], v168 offset:3072
	ds_read_b128 v[216:219], v168 offset:4096
	ds_read_b128 v[220:223], v168 offset:5120
	ds_read_b128 v[224:227], v168 offset:6144
	ds_read_b128 v[228:231], v168 offset:7168
	s_waitcnt vmcnt(8)
	s_waitcnt lgkmcnt(0)
	s_barrier
	s_setprio 1
	s_waitcnt lgkmcnt(0)
	v_mfma_f32_16x16x32_bf16 v[126:129], v[152:155], v[200:203], v[126:129]
	v_mfma_f32_16x16x32_bf16 v[126:129], v[172:175], v[204:207], v[126:129]
	v_mfma_f32_16x16x32_bf16 v[122:125], v[180:183], v[204:207], v[122:125]
	v_mfma_f32_16x16x32_bf16 v[122:125], v[176:179], v[200:203], v[122:125]
	v_mfma_f32_16x16x32_bf16 v[106:109], v[176:179], v[208:211], v[106:109]
	v_mfma_f32_16x16x32_bf16 v[106:109], v[180:183], v[212:215], v[106:109]
	v_mfma_f32_16x16x32_bf16 v[110:113], v[172:175], v[212:215], v[110:113]
	v_mfma_f32_16x16x32_bf16 v[110:113], v[152:155], v[208:211], v[110:113]
	v_mfma_f32_16x16x32_bf16 v[94:97], v[152:155], v[216:219], v[94:97]
	v_mfma_f32_16x16x32_bf16 v[94:97], v[172:175], v[220:223], v[94:97]
	v_mfma_f32_16x16x32_bf16 v[90:93], v[180:183], v[220:223], v[90:93]
	v_mfma_f32_16x16x32_bf16 v[90:93], v[176:179], v[216:219], v[90:93]
	v_mfma_f32_16x16x32_bf16 v[74:77], v[176:179], v[224:227], v[74:77]
	v_mfma_f32_16x16x32_bf16 v[74:77], v[180:183], v[228:231], v[74:77]
	v_mfma_f32_16x16x32_bf16 v[78:81], v[172:175], v[228:231], v[78:81]
	v_mfma_f32_16x16x32_bf16 v[78:81], v[152:155], v[224:227], v[78:81]
	s_setprio 0
	s_setprio 1
	v_mfma_f32_16x16x32_bf16 v[118:121], v[184:187], v[200:203], v[118:121]
	v_mfma_f32_16x16x32_bf16 v[118:121], v[188:191], v[204:207], v[118:121]
	v_mfma_f32_16x16x32_bf16 v[114:117], v[196:199], v[204:207], v[114:117]
	v_mfma_f32_16x16x32_bf16 v[114:117], v[192:195], v[200:203], v[114:117]
	v_mfma_f32_16x16x32_bf16 v[98:101], v[192:195], v[208:211], v[98:101]
	v_mfma_f32_16x16x32_bf16 v[98:101], v[196:199], v[212:215], v[98:101]
	v_mfma_f32_16x16x32_bf16 v[102:105], v[188:191], v[212:215], v[102:105]
	v_mfma_f32_16x16x32_bf16 v[102:105], v[184:187], v[208:211], v[102:105]
	v_mfma_f32_16x16x32_bf16 v[86:89], v[184:187], v[216:219], v[86:89]
	v_mfma_f32_16x16x32_bf16 v[86:89], v[188:191], v[220:223], v[86:89]
	v_mfma_f32_16x16x32_bf16 v[82:85], v[196:199], v[220:223], v[82:85]
	v_mfma_f32_16x16x32_bf16 v[82:85], v[192:195], v[216:219], v[82:85]
	v_mfma_f32_16x16x32_bf16 v[66:69], v[192:195], v[224:227], v[66:69]
	v_mfma_f32_16x16x32_bf16 v[66:69], v[196:199], v[228:231], v[66:69]
	v_mfma_f32_16x16x32_bf16 v[70:73], v[188:191], v[228:231], v[70:73]
	v_mfma_f32_16x16x32_bf16 v[70:73], v[184:187], v[224:227], v[70:73]
	s_setprio 0
	s_barrier
	s_add_i32 s23, s45, s3
	v_lshl_add_u64 v[156:157], s[26:27], 0, v[134:135]
	s_mov_b32 m0, s23
	s_nop 0
	global_load_lds_dwordx4 v[156:157], off
	s_add_i32 m0, s23, 0x2000
	v_lshl_add_u64 v[232:233], s[26:27], 0, v[130:131]
	global_load_lds_dwordx4 v[232:233], off
	s_add_u32 s48, s26, 0x80000
	s_addc_u32 s49, s27, 0
	s_add_i32 s23, s46, s3
	v_lshl_add_u64 v[234:235], s[48:49], 0, v[134:135]
	s_mov_b32 m0, s23
	s_nop 0
	global_load_lds_dwordx4 v[234:235], off
	v_lshl_add_u64 v[234:235], s[48:49], 0, v[130:131]
	s_add_i32 m0, s23, 0x2000
	s_nop 0
	global_load_lds_dwordx4 v[234:235], off
	v_lshl_add_u64 v[234:235], s[28:29], 0, v[136:137]
	s_mov_b32 m0, s34
	s_nop 0
	global_load_lds_dwordx4 v[234:235], off
	v_lshl_add_u64 v[236:237], s[28:29], 0, v[132:133]
	s_mov_b32 m0, s35
	s_nop 0
	global_load_lds_dwordx4 v[236:237], off
	ds_read_b128 v[200:203], v168 offset:16384
	ds_read_b128 v[204:207], v168 offset:17408
	ds_read_b128 v[208:211], v168 offset:18432
	ds_read_b128 v[212:215], v168 offset:19456
	ds_read_b128 v[216:219], v168 offset:20480
	ds_read_b128 v[220:223], v168 offset:21504
	ds_read_b128 v[224:227], v168 offset:22528
	ds_read_b128 v[228:231], v168 offset:23552
	s_waitcnt vmcnt(8)
	s_waitcnt lgkmcnt(0)
	s_barrier
; #define PG8_STAGE(bufoff, gbase, voff) do { _Pragma("unroll") for (int _i = 0; _i < 2; ++_i) \
;         __builtin_amdgcn_global_load_lds((const unsigned*)((const char*)(gbase) + (voff)[_i]), (PG8_LAS unsigned*)(lds + (bufoff) + ldsw + _i * 8192), 16, 0, 0); } while (0)
; #define PG8_LDA(dst, b, h) do { _Pragma("unroll") for (int m = 0; m < 4; ++m) _Pragma("unroll") for (int k = 0; k < 2; ++k) dst[m][k] = *(const PG8_LAS bf16x8*)(lds + PG8_SA(b, h) + aoff + m * 2048 + k * 1024); } while (0)
; #define PG8_LDB(dst, b, h) do { _Pragma("unroll") for (int n = 0; n < 2; ++n) _Pragma("unroll") for (int k = 0; k < 2; ++k) dst[n][k] = *(const PG8_LAS bf16x8*)(lds + PG8_SB(b, h) + boff + n * 2048 + k * 1024); } while (0)
; #define PG8_MMA(ai, bj, At, Bt) do { __builtin_amdgcn_s_setprio(1); _Pragma("unroll") for (int m = 0; m < 4; ++m) _Pragma("unroll") for (int n = 0; n < 2; ++n) _Pragma("unroll") for (int k = 0; k < 2; ++k) \
;         acc[ai][bj][m][n] = __builtin_amdgcn_mfma_f32_16x16x32_bf16(Bt[n][k], At[m][k], acc[ai][bj][m][n], 0, 0, 0); __builtin_amdgcn_s_setprio(0); } while (0)
; #define PG8_WAIT_V(n) asm volatile("s_waitcnt vmcnt(" #n ")" ::: "memory")
; #define PG8_WAIT_L(n) asm volatile("s_waitcnt lgkmcnt(" #n ")" ::: "memory")
; #define PG8_BAR __builtin_amdgcn_s_barrier()
; template <class Epi, class Sched, bool ALIGN_EPI>
; __device__ __forceinline__ void gemm_phase(PG8_LAS unsigned char* lds, const Gemm g, const Sched& S, const Epi& E) {
;     ...
;             PG8_WAIT_V(8); PG8_WAIT_L(0); PG8_BAR; PG8_MMA(0, 0, At, B0); PG8_MMA(0, 1, At, B1); PG8_BAR; PG8_SCHED;
;             PG8_LDA(At, 0, 1); PG8_STAGE(PG8_SB(0, 0), b2, voffB); PG8_STAGE(PG8_SB(0, 1), b2 + hstepB, voffB); PG8_STAGE(PG8_SA(0, 0), a2, voffA);
;             PG8_WAIT_V(8); PG8_WAIT_L(0); PG8_BAR; PG8_MMA(1, 0, At, B0); PG8_MMA(1, 1, At, B1); PG8_BAR; PG8_SCHED;
;             PG8_LDB(B0, 1, 0); PG8_LDB(B1, 1, 1); PG8_SCHED; PG8_LDA(At, 1, 0); PG8_STAGE(PG8_SA(0, 1), a2 + hstepA, voffA);
;             PG8_WAIT_V(8); PG8_WAIT_L(0); PG8_BAR; PG8_MMA(0, 0, At, B0); PG8_MMA(0, 1, At, B1); PG8_BAR; PG8_SCHED;
;             PG8_LDA(At, 1, 1); PG8_STAGE(PG8_SB(1, 0), b3, voffB); PG8_STAGE(PG8_SB(1, 1), b3 + hstepB, voffB); PG8_STAGE(PG8_SA(1, 0), a3, voffA);
;             PG8_WAIT_V(8); PG8_WAIT_L(0); PG8_BAR; PG8_MMA(1, 0, At, B0); PG8_MMA(1, 1, At, B1); PG8_BAR; PG8_SCHED;
	s_setprio 1
	s_waitcnt lgkmcnt(0)
	v_mfma_f32_16x16x32_bf16 v[62:65], v[152:155], v[200:203], v[62:65]
	v_mfma_f32_16x16x32_bf16 v[62:65], v[172:175], v[204:207], v[62:65]
	v_mfma_f32_16x16x32_bf16 v[58:61], v[180:183], v[204:207], v[58:61]
	v_mfma_f32_16x16x32_bf16 v[58:61], v[176:179], v[200:203], v[58:61]
	v_mfma_f32_16x16x32_bf16 v[42:45], v[176:179], v[208:211], v[42:45]
	v_mfma_f32_16x16x32_bf16 v[42:45], v[180:183], v[212:215], v[42:45]
	v_mfma_f32_16x16x32_bf16 v[46:49], v[172:175], v[212:215], v[46:49]
	v_mfma_f32_16x16x32_bf16 v[46:49], v[152:155], v[208:211], v[46:49]
	v_mfma_f32_16x16x32_bf16 v[30:33], v[152:155], v[216:219], v[30:33]
	v_mfma_f32_16x16x32_bf16 v[30:33], v[172:175], v[220:223], v[30:33]
	v_mfma_f32_16x16x32_bf16 v[26:29], v[180:183], v[220:223], v[26:29]
	v_mfma_f32_16x16x32_bf16 v[26:29], v[176:179], v[216:219], v[26:29]
	v_mfma_f32_16x16x32_bf16 v[10:13], v[176:179], v[224:227], v[10:13]
	v_mfma_f32_16x16x32_bf16 v[10:13], v[180:183], v[228:231], v[10:13]
	v_mfma_f32_16x16x32_bf16 v[14:17], v[172:175], v[228:231], v[14:17]
	v_mfma_f32_16x16x32_bf16 v[14:17], v[152:155], v[224:227], v[14:17]
	s_setprio 0
	s_setprio 1
	v_mfma_f32_16x16x32_bf16 v[54:57], v[184:187], v[200:203], v[54:57]
	v_mfma_f32_16x16x32_bf16 v[54:57], v[188:191], v[204:207], v[54:57]
	v_mfma_f32_16x16x32_bf16 v[50:53], v[196:199], v[204:207], v[50:53]
	v_mfma_f32_16x16x32_bf16 v[50:53], v[192:195], v[200:203], v[50:53]
	v_mfma_f32_16x16x32_bf16 v[34:37], v[192:195], v[208:211], v[34:37]
	v_mfma_f32_16x16x32_bf16 v[34:37], v[196:199], v[212:215], v[34:37]
	v_mfma_f32_16x16x32_bf16 v[38:41], v[188:191], v[212:215], v[38:41]
	v_mfma_f32_16x16x32_bf16 v[38:41], v[184:187], v[208:211], v[38:41]
	v_mfma_f32_16x16x32_bf16 v[22:25], v[184:187], v[216:219], v[22:25]
	v_mfma_f32_16x16x32_bf16 v[22:25], v[188:191], v[220:223], v[22:25]
	v_mfma_f32_16x16x32_bf16 v[18:21], v[196:199], v[220:223], v[18:21]
	v_mfma_f32_16x16x32_bf16 v[18:21], v[192:195], v[216:219], v[18:21]
	v_mfma_f32_16x16x32_bf16 v[2:5], v[192:195], v[224:227], v[2:5]
	v_mfma_f32_16x16x32_bf16 v[2:5], v[196:199], v[228:231], v[2:5]
	v_mfma_f32_16x16x32_bf16 v[6:9], v[188:191], v[228:231], v[6:9]
	v_mfma_f32_16x16x32_bf16 v[6:9], v[184:187], v[224:227], v[6:9]
	s_setprio 0
	s_barrier
	s_add_i32 s23, 0, 0x18000
	s_add_i32 s48, 0, 0x1c000
	s_add_u32 s28, s28, 0x80000
	s_addc_u32 s29, s29, 0
	s_mov_b32 m0, s36
	v_lshl_add_u64 v[238:239], s[28:29], 0, v[136:137]
	global_load_lds_dwordx4 v[238:239], off
	v_lshl_add_u64 v[238:239], s[28:29], 0, v[132:133]
	s_mov_b32 m0, s37
	s_nop 0
	global_load_lds_dwordx4 v[238:239], off
	v_add_u32_e32 v149, s23, v159
	ds_read_b128 v[152:155], v149
	ds_read_b128 v[172:175], v149 offset:1024
	ds_read_b128 v[176:179], v149 offset:2048
	ds_read_b128 v[180:183], v149 offset:3072
	v_add_u32_e32 v149, s48, v159
	ds_read_b128 v[184:187], v149
	ds_read_b128 v[188:191], v149 offset:1024
	ds_read_b128 v[192:195], v149 offset:2048
	ds_read_b128 v[196:199], v149 offset:3072
	ds_read_b128 v[200:203], v168 offset:32768
	ds_read_b128 v[204:207], v168 offset:33792
	ds_read_b128 v[208:211], v168 offset:34816
	ds_read_b128 v[212:215], v168 offset:35840
	ds_read_b128 v[216:219], v168 offset:36864
	ds_read_b128 v[220:223], v168 offset:37888
	ds_read_b128 v[224:227], v168 offset:38912
	ds_read_b128 v[228:231], v168 offset:39936
	s_waitcnt vmcnt(8)
	s_waitcnt lgkmcnt(0)
	s_barrier
	s_setprio 1
	s_waitcnt lgkmcnt(0)
	v_mfma_f32_16x16x32_bf16 v[126:129], v[152:155], v[200:203], v[126:129]
	v_mfma_f32_16x16x32_bf16 v[126:129], v[172:175], v[204:207], v[126:129]
	v_mfma_f32_16x16x32_bf16 v[122:125], v[180:183], v[204:207], v[122:125]
	v_mfma_f32_16x16x32_bf16 v[122:125], v[176:179], v[200:203], v[122:125]
	v_mfma_f32_16x16x32_bf16 v[106:109], v[176:179], v[208:211], v[106:109]
	v_mfma_f32_16x16x32_bf16 v[106:109], v[180:183], v[212:215], v[106:109]
	v_mfma_f32_16x16x32_bf16 v[110:113], v[172:175], v[212:215], v[110:113]
	v_mfma_f32_16x16x32_bf16 v[110:113], v[152:155], v[208:211], v[110:113]
	v_mfma_f32_16x16x32_bf16 v[94:97], v[152:155], v[216:219], v[94:97]
	v_mfma_f32_16x16x32_bf16 v[94:97], v[172:175], v[220:223], v[94:97]
	v_mfma_f32_16x16x32_bf16 v[90:93], v[180:183], v[220:223], v[90:93]
	v_mfma_f32_16x16x32_bf16 v[90:93], v[176:179], v[216:219], v[90:93]
	v_mfma_f32_16x16x32_bf16 v[74:77], v[176:179], v[224:227], v[74:77]
	v_mfma_f32_16x16x32_bf16 v[74:77], v[180:183], v[228:231], v[74:77]
	v_mfma_f32_16x16x32_bf16 v[78:81], v[172:175], v[228:231], v[78:81]
	v_mfma_f32_16x16x32_bf16 v[78:81], v[152:155], v[224:227], v[78:81]
	s_setprio 0
	s_setprio 1
	v_mfma_f32_16x16x32_bf16 v[118:121], v[184:187], v[200:203], v[118:121]
	v_mfma_f32_16x16x32_bf16 v[118:121], v[188:191], v[204:207], v[118:121]
	v_mfma_f32_16x16x32_bf16 v[114:117], v[196:199], v[204:207], v[114:117]
	v_mfma_f32_16x16x32_bf16 v[114:117], v[192:195], v[200:203], v[114:117]
	v_mfma_f32_16x16x32_bf16 v[98:101], v[192:195], v[208:211], v[98:101]
	v_mfma_f32_16x16x32_bf16 v[98:101], v[196:199], v[212:215], v[98:101]
	v_mfma_f32_16x16x32_bf16 v[102:105], v[188:191], v[212:215], v[102:105]
	v_mfma_f32_16x16x32_bf16 v[102:105], v[184:187], v[208:211], v[102:105]
	v_mfma_f32_16x16x32_bf16 v[86:89], v[184:187], v[216:219], v[86:89]
	v_mfma_f32_16x16x32_bf16 v[86:89], v[188:191], v[220:223], v[86:89]
	v_mfma_f32_16x16x32_bf16 v[82:85], v[196:199], v[220:223], v[82:85]
	v_mfma_f32_16x16x32_bf16 v[82:85], v[192:195], v[216:219], v[82:85]
	v_mfma_f32_16x16x32_bf16 v[66:69], v[192:195], v[224:227], v[66:69]
	v_mfma_f32_16x16x32_bf16 v[66:69], v[196:199], v[228:231], v[66:69]
	v_mfma_f32_16x16x32_bf16 v[70:73], v[188:191], v[228:231], v[70:73]
	v_mfma_f32_16x16x32_bf16 v[70:73], v[184:187], v[224:227], v[70:73]
	s_setprio 0
	s_barrier
; #define PG8_STAGE(bufoff, gbase, voff) do { _Pragma("unroll") for (int _i = 0; _i < 2; ++_i) \
;         __builtin_amdgcn_global_load_lds((const unsigned*)((const char*)(gbase) + (voff)[_i]), (PG8_LAS unsigned*)(lds + (bufoff) + ldsw + _i * 8192), 16, 0, 0); } while (0)
; #define PG8_LDA(dst, b, h) do { _Pragma("unroll") for (int m = 0; m < 4; ++m) _Pragma("unroll") for (int k = 0; k < 2; ++k) dst[m][k] = *(const PG8_LAS bf16x8*)(lds + PG8_SA(b, h) + aoff + m * 2048 + k * 1024); } while (0)
; #define PG8_MMA(ai, bj, At, Bt) do { __builtin_amdgcn_s_setprio(1); _Pragma("unroll") for (int m = 0; m < 4; ++m) _Pragma("unroll") for (int n = 0; n < 2; ++n) _Pragma("unroll") for (int k = 0; k < 2; ++k) \
;         acc[ai][bj][m][n] = __builtin_amdgcn_mfma_f32_16x16x32_bf16(Bt[n][k], At[m][k], acc[ai][bj][m][n], 0, 0, 0); __builtin_amdgcn_s_setprio(0); } while (0)
; #define PG8_WAIT_V(n) asm volatile("s_waitcnt vmcnt(" #n ")" ::: "memory")
; #define PG8_WAIT_L(n) asm volatile("s_waitcnt lgkmcnt(" #n ")" ::: "memory")
; #define PG8_BAR __builtin_amdgcn_s_barrier()
; #define PG8_SCHED __builtin_amdgcn_sched_barrier(0)
; template <class Epi, class Sched, bool ALIGN_EPI>
; __device__ __forceinline__ void gemm_phase(PG8_LAS unsigned char* lds, const Gemm g, const Sched& S, const Epi& E) {
;     ...
;         for (int t = 0; t < nt; t += 2) {
;     ...
;             PG8_LDA(At, 1, 1); PG8_STAGE(PG8_SB(1, 0), b3, voffB); PG8_STAGE(PG8_SB(1, 1), b3 + hstepB, voffB); PG8_STAGE(PG8_SA(1, 0), a3, voffA);
;             PG8_WAIT_V(8); PG8_WAIT_L(0); PG8_BAR; PG8_MMA(1, 0, At, B0); PG8_MMA(1, 1, At, B1); PG8_BAR; PG8_SCHED;
	s_add_i32 s23, s23, s3
	v_lshl_add_u64 v[156:157], v[156:157], 0, s[8:9]
	s_mov_b32 m0, s23
	s_nop 0
	global_load_lds_dwordx4 v[156:157], off
	s_add_i32 m0, s23, 0x2000
	v_lshl_add_u64 v[156:157], v[232:233], 0, s[8:9]
	global_load_lds_dwordx4 v[156:157], off
	s_add_u32 s26, s26, 0x80080
	s_addc_u32 s27, s27, 0
	s_add_i32 s23, s48, s3
	v_lshl_add_u64 v[156:157], s[26:27], 0, v[134:135]
	s_mov_b32 m0, s23
	s_nop 0
	global_load_lds_dwordx4 v[156:157], off
	v_lshl_add_u64 v[156:157], s[26:27], 0, v[130:131]
	s_add_i32 m0, s23, 0x2000
	s_nop 0
	global_load_lds_dwordx4 v[156:157], off
	v_lshl_add_u64 v[156:157], v[234:235], 0, s[8:9]
	s_mov_b32 m0, s42
	s_nop 0
	global_load_lds_dwordx4 v[156:157], off
	v_lshl_add_u64 v[156:157], v[236:237], 0, s[8:9]
	s_mov_b32 m0, s43
	s_nop 0
	global_load_lds_dwordx4 v[156:157], off
	ds_read_b128 v[200:203], v168 offset:49152
	ds_read_b128 v[204:207], v168 offset:50176
	ds_read_b128 v[208:211], v168 offset:51200
	ds_read_b128 v[212:215], v168 offset:52224
	ds_read_b128 v[216:219], v168 offset:53248
	ds_read_b128 v[220:223], v168 offset:54272
	ds_read_b128 v[224:227], v168 offset:55296
	ds_read_b128 v[228:231], v168 offset:56320
	s_waitcnt vmcnt(8)
	s_waitcnt lgkmcnt(0)
	s_barrier
	s_setprio 1
	s_waitcnt lgkmcnt(0)
	v_mfma_f32_16x16x32_bf16 v[62:65], v[152:155], v[200:203], v[62:65]
	v_mfma_f32_16x16x32_bf16 v[62:65], v[172:175], v[204:207], v[62:65]
	v_mfma_f32_16x16x32_bf16 v[58:61], v[180:183], v[204:207], v[58:61]
	v_mfma_f32_16x16x32_bf16 v[58:61], v[176:179], v[200:203], v[58:61]
	v_mfma_f32_16x16x32_bf16 v[42:45], v[176:179], v[208:211], v[42:45]
	v_mfma_f32_16x16x32_bf16 v[42:45], v[180:183], v[212:215], v[42:45]
	v_mfma_f32_16x16x32_bf16 v[46:49], v[172:175], v[212:215], v[46:49]
	v_mfma_f32_16x16x32_bf16 v[46:49], v[152:155], v[208:211], v[46:49]
	v_mfma_f32_16x16x32_bf16 v[30:33], v[152:155], v[216:219], v[30:33]
	v_mfma_f32_16x16x32_bf16 v[30:33], v[172:175], v[220:223], v[30:33]
	v_mfma_f32_16x16x32_bf16 v[26:29], v[180:183], v[220:223], v[26:29]
	v_mfma_f32_16x16x32_bf16 v[26:29], v[176:179], v[216:219], v[26:29]
	v_mfma_f32_16x16x32_bf16 v[10:13], v[176:179], v[224:227], v[10:13]
	v_mfma_f32_16x16x32_bf16 v[10:13], v[180:183], v[228:231], v[10:13]
	v_mfma_f32_16x16x32_bf16 v[14:17], v[172:175], v[228:231], v[14:17]
	v_mfma_f32_16x16x32_bf16 v[14:17], v[152:155], v[224:227], v[14:17]
	s_setprio 0
	s_setprio 1
	v_mfma_f32_16x16x32_bf16 v[54:57], v[184:187], v[200:203], v[54:57]
	v_mfma_f32_16x16x32_bf16 v[54:57], v[188:191], v[204:207], v[54:57]
	v_mfma_f32_16x16x32_bf16 v[50:53], v[196:199], v[204:207], v[50:53]
	v_mfma_f32_16x16x32_bf16 v[50:53], v[192:195], v[200:203], v[50:53]
	v_mfma_f32_16x16x32_bf16 v[34:37], v[192:195], v[208:211], v[34:37]
	v_mfma_f32_16x16x32_bf16 v[34:37], v[196:199], v[212:215], v[34:37]
	v_mfma_f32_16x16x32_bf16 v[38:41], v[188:191], v[212:215], v[38:41]
	v_mfma_f32_16x16x32_bf16 v[38:41], v[184:187], v[208:211], v[38:41]
	v_mfma_f32_16x16x32_bf16 v[22:25], v[184:187], v[216:219], v[22:25]
	v_mfma_f32_16x16x32_bf16 v[22:25], v[188:191], v[220:223], v[22:25]
	v_mfma_f32_16x16x32_bf16 v[18:21], v[196:199], v[220:223], v[18:21]
	v_mfma_f32_16x16x32_bf16 v[18:21], v[192:195], v[216:219], v[18:21]
	v_mfma_f32_16x16x32_bf16 v[2:5], v[192:195], v[224:227], v[2:5]
	v_mfma_f32_16x16x32_bf16 v[2:5], v[196:199], v[228:231], v[2:5]
	v_mfma_f32_16x16x32_bf16 v[6:9], v[188:191], v[228:231], v[6:9]
	v_mfma_f32_16x16x32_bf16 v[6:9], v[184:187], v[224:227], v[6:9]
	s_setprio 0
	s_barrier
	s_add_i32 s17, s17, 2
	s_add_u32 s24, s24, 0x100
	s_addc_u32 s25, s25, 0
	s_add_u32 s5, s5, 0x100
	s_addc_u32 s15, s15, 0
	s_cmp_gt_u32 s17, 29
	s_cbranch_scc0 .LBB0_403
	s_and_b64 vcc, exec, s[10:11]
	s_cbranch_vccz .LBB0_406
	s_barrier

; #define PG8_STAGE(bufoff, gbase, voff) do { _Pragma("unroll") for (int _i = 0; _i < 2; ++_i) \
;         __builtin_amdgcn_global_load_lds((const unsigned*)((const char*)(gbase) + (voff)[_i]), (PG8_LAS unsigned*)(lds + (bufoff) + ldsw + _i * 8192), 16, 0, 0); } while (0)
; #define PG8_LDA(dst, b, h) do { _Pragma("unroll") for (int m = 0; m < 4; ++m) _Pragma("unroll") for (int k = 0; k < 2; ++k) dst[m][k] = *(const PG8_LAS bf16x8*)(lds + PG8_SA(b, h) + aoff + m * 2048 + k * 1024); } while (0)
; #define PG8_LDB(dst, b, h) do { _Pragma("unroll") for (int n = 0; n < 2; ++n) _Pragma("unroll") for (int k = 0; k < 2; ++k) dst[n][k] = *(const PG8_LAS bf16x8*)(lds + PG8_SB(b, h) + boff + n * 2048 + k * 1024); } while (0)
; #define PG8_MMA(ai, bj, At, Bt) do { __builtin_amdgcn_s_setprio(1); _Pragma("unroll") for (int m = 0; m < 4; ++m) _Pragma("unroll") for (int n = 0; n < 2; ++n) _Pragma("unroll") for (int k = 0; k < 2; ++k) \
;         acc[ai][bj][m][n] = __builtin_amdgcn_mfma_f32_16x16x32_bf16(Bt[n][k], At[m][k], acc[ai][bj][m][n], 0, 0, 0); __builtin_amdgcn_s_setprio(0); } while (0)
; #define PG8_WAIT_V(n) asm volatile("s_waitcnt vmcnt(" #n ")" ::: "memory")
; #define PG8_WAIT_L(n) asm volatile("s_waitcnt lgkmcnt(" #n ")" ::: "memory")
; #define PG8_BAR __builtin_amdgcn_s_barrier()
; #define PG8_SCHED __builtin_amdgcn_sched_barrier(0)
; template <class Epi, class Sched, bool ALIGN_EPI>
; __device__ __forceinline__ void gemm_phase(PG8_LAS unsigned char* lds, const Gemm g, const Sched& S, const Epi& E) {
;     ...
;             const char* a1 = cA + (size_t)(t + 1) * kstepA;
;             const char* a2 = last ? nA : cA + (size_t)(t + 2) * kstepA; const char* b2 = last ? nB : cB + (size_t)(t + 2) * kstep;
;             const char* a3 = a2 + kstepA; const char* b3 = b2 + kstep;
;             PG8_LDB(B0, 0, 0); PG8_LDB(B1, 0, 1); PG8_SCHED; PG8_LDA(At, 0, 0); PG8_STAGE(PG8_SA(1, 1), a1 + hstepA, voffA);
;             PG8_WAIT_V(8); PG8_WAIT_L(0); PG8_BAR; PG8_MMA(0, 0, At, B0); PG8_MMA(0, 1, At, B1); PG8_BAR; PG8_SCHED;
;             PG8_LDA(At, 0, 1); PG8_STAGE(PG8_SB(0, 0), b2, voffB); PG8_STAGE(PG8_SB(0, 1), b2 + hstepB, voffB); PG8_STAGE(PG8_SA(0, 0), a2, voffA);
;             PG8_WAIT_V(8); PG8_WAIT_L(0); PG8_BAR; PG8_MMA(1, 0, At, B0); PG8_MMA(1, 1, At, B1); PG8_BAR; PG8_SCHED;
.LBB0_431:
	s_add_u32 s34, s30, 0xfff80080
	s_addc_u32 s35, s31, -1
	s_cmp_eq_u32 s54, 28
	s_cselect_b32 s37, s25, s35
	s_cselect_b32 s36, s24, s34
	s_cselect_b32 s35, s27, s23
	s_cselect_b32 s34, s26, s21
	v_lshl_add_u64 v[142:143], s[30:31], 0, v[138:139]
	s_add_i32 m0, s29, 0xc000
	s_nop 0
	global_load_lds_dwordx4 v[142:143], off
	v_lshl_add_u64 v[142:143], s[30:31], 0, v[140:141]
	s_add_i32 m0, s29, 0xe000
	s_nop 0
	global_load_lds_dwordx4 v[142:143], off
	ds_read_b128 v[150:153], v147
	ds_read_b128 v[154:157], v147 offset:1024
	ds_read_b128 v[158:161], v147 offset:2048
	ds_read_b128 v[162:165], v147 offset:3072
	ds_read_b128 v[166:169], v148
	ds_read_b128 v[170:173], v148 offset:1024
	ds_read_b128 v[174:177], v148 offset:2048
	ds_read_b128 v[178:181], v148 offset:3072
	ds_read_b128 v[182:185], v149
	ds_read_b128 v[186:189], v149 offset:1024
	ds_read_b128 v[190:193], v149 offset:2048
	ds_read_b128 v[194:197], v149 offset:3072
	ds_read_b128 v[198:201], v149 offset:4096
	ds_read_b128 v[202:205], v149 offset:5120
	ds_read_b128 v[206:209], v149 offset:6144
	ds_read_b128 v[210:213], v149 offset:7168
	s_waitcnt vmcnt(8)
	s_waitcnt lgkmcnt(0)
	s_barrier
	s_setprio 1
	s_waitcnt lgkmcnt(0)
	v_mfma_f32_16x16x32_bf16 v[126:129], v[150:153], v[182:185], v[126:129]
	v_mfma_f32_16x16x32_bf16 v[126:129], v[154:157], v[186:189], v[126:129]
	v_mfma_f32_16x16x32_bf16 v[122:125], v[162:165], v[186:189], v[122:125]
	v_mfma_f32_16x16x32_bf16 v[122:125], v[158:161], v[182:185], v[122:125]
	v_mfma_f32_16x16x32_bf16 v[110:113], v[158:161], v[190:193], v[110:113]
	v_mfma_f32_16x16x32_bf16 v[110:113], v[162:165], v[194:197], v[110:113]
	v_mfma_f32_16x16x32_bf16 v[118:121], v[154:157], v[194:197], v[118:121]
	v_mfma_f32_16x16x32_bf16 v[118:121], v[150:153], v[190:193], v[118:121]
	v_mfma_f32_16x16x32_bf16 v[102:105], v[150:153], v[198:201], v[102:105]
	v_mfma_f32_16x16x32_bf16 v[102:105], v[154:157], v[202:205], v[102:105]
	v_mfma_f32_16x16x32_bf16 v[94:97], v[162:165], v[202:205], v[94:97]
	v_mfma_f32_16x16x32_bf16 v[94:97], v[158:161], v[198:201], v[94:97]
	v_mfma_f32_16x16x32_bf16 v[78:81], v[158:161], v[206:209], v[78:81]
	v_mfma_f32_16x16x32_bf16 v[78:81], v[162:165], v[210:213], v[78:81]
	v_mfma_f32_16x16x32_bf16 v[86:89], v[154:157], v[210:213], v[86:89]
	v_mfma_f32_16x16x32_bf16 v[86:89], v[150:153], v[206:209], v[86:89]
	s_setprio 0
	s_setprio 1
	v_mfma_f32_16x16x32_bf16 v[114:117], v[166:169], v[182:185], v[114:117]
	v_mfma_f32_16x16x32_bf16 v[114:117], v[170:173], v[186:189], v[114:117]
	v_mfma_f32_16x16x32_bf16 v[106:109], v[178:181], v[186:189], v[106:109]
	v_mfma_f32_16x16x32_bf16 v[106:109], v[174:177], v[182:185], v[106:109]
	v_mfma_f32_16x16x32_bf16 v[90:93], v[174:177], v[190:193], v[90:93]
	v_mfma_f32_16x16x32_bf16 v[90:93], v[178:181], v[194:197], v[90:93]
	v_mfma_f32_16x16x32_bf16 v[98:101], v[170:173], v[194:197], v[98:101]
	v_mfma_f32_16x16x32_bf16 v[98:101], v[166:169], v[190:193], v[98:101]
	v_mfma_f32_16x16x32_bf16 v[82:85], v[166:169], v[198:201], v[82:85]
	v_mfma_f32_16x16x32_bf16 v[82:85], v[170:173], v[202:205], v[82:85]
	v_mfma_f32_16x16x32_bf16 v[74:77], v[178:181], v[202:205], v[74:77]
	v_mfma_f32_16x16x32_bf16 v[74:77], v[174:177], v[198:201], v[74:77]
	v_mfma_f32_16x16x32_bf16 v[66:69], v[174:177], v[206:209], v[66:69]
	v_mfma_f32_16x16x32_bf16 v[66:69], v[178:181], v[210:213], v[66:69]
	v_mfma_f32_16x16x32_bf16 v[70:73], v[170:173], v[210:213], v[70:73]
	v_mfma_f32_16x16x32_bf16 v[70:73], v[166:169], v[206:209], v[70:73]
	s_setprio 0
	s_barrier
	s_add_i32 s55, s47, s39
	v_lshl_add_u64 v[142:143], s[34:35], 0, v[132:133]
	s_mov_b32 m0, s55
	s_nop 0
	global_load_lds_dwordx4 v[142:143], off
	s_add_i32 m0, s55, 0x2000
	v_lshl_add_u64 v[214:215], s[34:35], 0, v[136:137]
	global_load_lds_dwordx4 v[214:215], off
	s_add_u32 s56, s34, 0x80000
	s_addc_u32 s57, s35, 0
	s_add_i32 s55, s48, s39
	v_lshl_add_u64 v[216:217], s[56:57], 0, v[132:133]
	s_mov_b32 m0, s55
	s_nop 0
	global_load_lds_dwordx4 v[216:217], off
	v_lshl_add_u64 v[216:217], s[56:57], 0, v[136:137]
	s_add_i32 m0, s55, 0x2000
	s_nop 0
	global_load_lds_dwordx4 v[216:217], off
	v_lshl_add_u64 v[216:217], s[36:37], 0, v[130:131]
	s_mov_b32 m0, s29
	s_nop 0
	global_load_lds_dwordx4 v[216:217], off
	v_lshl_add_u64 v[218:219], s[36:37], 0, v[134:135]
	s_mov_b32 m0, s40
	s_nop 0
	global_load_lds_dwordx4 v[218:219], off
	ds_read_b128 v[182:185], v149 offset:16384
	ds_read_b128 v[186:189], v149 offset:17408
	ds_read_b128 v[190:193], v149 offset:18432
	ds_read_b128 v[194:197], v149 offset:19456
	ds_read_b128 v[198:201], v149 offset:20480
	ds_read_b128 v[202:205], v149 offset:21504
	ds_read_b128 v[206:209], v149 offset:22528
	ds_read_b128 v[210:213], v149 offset:23552
	s_waitcnt vmcnt(8)
	s_waitcnt lgkmcnt(0)
	s_barrier
; #define PG8_STAGE(bufoff, gbase, voff) do { _Pragma("unroll") for (int _i = 0; _i < 2; ++_i) \
;         __builtin_amdgcn_global_load_lds((const unsigned*)((const char*)(gbase) + (voff)[_i]), (PG8_LAS unsigned*)(lds + (bufoff) + ldsw + _i * 8192), 16, 0, 0); } while (0)
; #define PG8_LDA(dst, b, h) do { _Pragma("unroll") for (int m = 0; m < 4; ++m) _Pragma("unroll") for (int k = 0; k < 2; ++k) dst[m][k] = *(const PG8_LAS bf16x8*)(lds + PG8_SA(b, h) + aoff + m * 2048 + k * 1024); } while (0)
; #define PG8_LDB(dst, b, h) do { _Pragma("unroll") for (int n = 0; n < 2; ++n) _Pragma("unroll") for (int k = 0; k < 2; ++k) dst[n][k] = *(const PG8_LAS bf16x8*)(lds + PG8_SB(b, h) + boff + n * 2048 + k * 1024); } while (0)
; #define PG8_MMA(ai, bj, At, Bt) do { __builtin_amdgcn_s_setprio(1); _Pragma("unroll") for (int m = 0; m < 4; ++m) _Pragma("unroll") for (int n = 0; n < 2; ++n) _Pragma("unroll") for (int k = 0; k < 2; ++k) \
;         acc[ai][bj][m][n] = __builtin_amdgcn_mfma_f32_16x16x32_bf16(Bt[n][k], At[m][k], acc[ai][bj][m][n], 0, 0, 0); __builtin_amdgcn_s_setprio(0); } while (0)
; #define PG8_WAIT_V(n) asm volatile("s_waitcnt vmcnt(" #n ")" ::: "memory")
; #define PG8_WAIT_L(n) asm volatile("s_waitcnt lgkmcnt(" #n ")" ::: "memory")
; #define PG8_BAR __builtin_amdgcn_s_barrier()
; template <class Epi, class Sched, bool ALIGN_EPI>
; __device__ __forceinline__ void gemm_phase(PG8_LAS unsigned char* lds, const Gemm g, const Sched& S, const Epi& E) {
;     ...
;             PG8_WAIT_V(8); PG8_WAIT_L(0); PG8_BAR; PG8_MMA(0, 0, At, B0); PG8_MMA(0, 1, At, B1); PG8_BAR; PG8_SCHED;
;             PG8_LDA(At, 0, 1); PG8_STAGE(PG8_SB(0, 0), b2, voffB); PG8_STAGE(PG8_SB(0, 1), b2 + hstepB, voffB); PG8_STAGE(PG8_SA(0, 0), a2, voffA);
;             PG8_WAIT_V(8); PG8_WAIT_L(0); PG8_BAR; PG8_MMA(1, 0, At, B0); PG8_MMA(1, 1, At, B1); PG8_BAR; PG8_SCHED;
;             PG8_LDB(B0, 1, 0); PG8_LDB(B1, 1, 1); PG8_SCHED; PG8_LDA(At, 1, 0); PG8_STAGE(PG8_SA(0, 1), a2 + hstepA, voffA);
;             PG8_WAIT_V(8); PG8_WAIT_L(0); PG8_BAR; PG8_MMA(0, 0, At, B0); PG8_MMA(0, 1, At, B1); PG8_BAR; PG8_SCHED;
;             PG8_LDA(At, 1, 1); PG8_STAGE(PG8_SB(1, 0), b3, voffB); PG8_STAGE(PG8_SB(1, 1), b3 + hstepB, voffB); PG8_STAGE(PG8_SA(1, 0), a3, voffA);
;             PG8_WAIT_V(8); PG8_WAIT_L(0); PG8_BAR; PG8_MMA(1, 0, At, B0); PG8_MMA(1, 1, At, B1); PG8_BAR; PG8_SCHED;
	s_setprio 1
	s_waitcnt lgkmcnt(0)
	v_mfma_f32_16x16x32_bf16 v[62:65], v[150:153], v[182:185], v[62:65]
	v_mfma_f32_16x16x32_bf16 v[62:65], v[154:157], v[186:189], v[62:65]
	v_mfma_f32_16x16x32_bf16 v[58:61], v[162:165], v[186:189], v[58:61]
	v_mfma_f32_16x16x32_bf16 v[58:61], v[158:161], v[182:185], v[58:61]
	v_mfma_f32_16x16x32_bf16 v[46:49], v[158:161], v[190:193], v[46:49]
	v_mfma_f32_16x16x32_bf16 v[46:49], v[162:165], v[194:197], v[46:49]
	v_mfma_f32_16x16x32_bf16 v[54:57], v[154:157], v[194:197], v[54:57]
	v_mfma_f32_16x16x32_bf16 v[54:57], v[150:153], v[190:193], v[54:57]
	v_mfma_f32_16x16x32_bf16 v[38:41], v[150:153], v[198:201], v[38:41]
	v_mfma_f32_16x16x32_bf16 v[38:41], v[154:157], v[202:205], v[38:41]
	v_mfma_f32_16x16x32_bf16 v[30:33], v[162:165], v[202:205], v[30:33]
	v_mfma_f32_16x16x32_bf16 v[30:33], v[158:161], v[198:201], v[30:33]
	v_mfma_f32_16x16x32_bf16 v[14:17], v[158:161], v[206:209], v[14:17]
	v_mfma_f32_16x16x32_bf16 v[14:17], v[162:165], v[210:213], v[14:17]
	v_mfma_f32_16x16x32_bf16 v[22:25], v[154:157], v[210:213], v[22:25]
	v_mfma_f32_16x16x32_bf16 v[22:25], v[150:153], v[206:209], v[22:25]
	s_setprio 0
	s_setprio 1
	v_mfma_f32_16x16x32_bf16 v[50:53], v[166:169], v[182:185], v[50:53]
	v_mfma_f32_16x16x32_bf16 v[50:53], v[170:173], v[186:189], v[50:53]
	v_mfma_f32_16x16x32_bf16 v[42:45], v[178:181], v[186:189], v[42:45]
	v_mfma_f32_16x16x32_bf16 v[42:45], v[174:177], v[182:185], v[42:45]
	v_mfma_f32_16x16x32_bf16 v[26:29], v[174:177], v[190:193], v[26:29]
	v_mfma_f32_16x16x32_bf16 v[26:29], v[178:181], v[194:197], v[26:29]
	v_mfma_f32_16x16x32_bf16 v[34:37], v[170:173], v[194:197], v[34:37]
	v_mfma_f32_16x16x32_bf16 v[34:37], v[166:169], v[190:193], v[34:37]
	v_mfma_f32_16x16x32_bf16 v[18:21], v[166:169], v[198:201], v[18:21]
	v_mfma_f32_16x16x32_bf16 v[18:21], v[170:173], v[202:205], v[18:21]
	v_mfma_f32_16x16x32_bf16 v[10:13], v[178:181], v[202:205], v[10:13]
	v_mfma_f32_16x16x32_bf16 v[10:13], v[174:177], v[198:201], v[10:13]
	v_mfma_f32_16x16x32_bf16 v[2:5], v[174:177], v[206:209], v[2:5]
	v_mfma_f32_16x16x32_bf16 v[2:5], v[178:181], v[210:213], v[2:5]
	v_mfma_f32_16x16x32_bf16 v[6:9], v[170:173], v[210:213], v[6:9]
	v_mfma_f32_16x16x32_bf16 v[6:9], v[166:169], v[206:209], v[6:9]
	s_setprio 0
	s_barrier
	s_add_i32 s55, 0, 0x18000
	s_add_i32 s56, 0, 0x1c000
	s_add_u32 s36, s36, 0x80000
	s_addc_u32 s37, s37, 0
	s_mov_b32 m0, s41
	v_lshl_add_u64 v[220:221], s[36:37], 0, v[130:131]
	global_load_lds_dwordx4 v[220:221], off
	v_lshl_add_u64 v[220:221], s[36:37], 0, v[134:135]
	s_mov_b32 m0, s42
	s_nop 0
	global_load_lds_dwordx4 v[220:221], off
	v_add_u32_e32 v162, s55, v145
	ds_read_b128 v[150:153], v162
	ds_read_b128 v[154:157], v162 offset:1024
	ds_read_b128 v[158:161], v162 offset:2048
	ds_read_b128 v[162:165], v162 offset:3072
	v_add_u32_e32 v178, s56, v145
	ds_read_b128 v[166:169], v178
	ds_read_b128 v[170:173], v178 offset:1024
	ds_read_b128 v[174:177], v178 offset:2048
	ds_read_b128 v[178:181], v178 offset:3072
	ds_read_b128 v[182:185], v149 offset:32768
	ds_read_b128 v[186:189], v149 offset:33792
	ds_read_b128 v[190:193], v149 offset:34816
	ds_read_b128 v[194:197], v149 offset:35840
	ds_read_b128 v[198:201], v149 offset:36864
	ds_read_b128 v[202:205], v149 offset:37888
	ds_read_b128 v[206:209], v149 offset:38912
	ds_read_b128 v[210:213], v149 offset:39936
	s_waitcnt vmcnt(8)
	s_waitcnt lgkmcnt(0)
	s_barrier
	s_setprio 1
	s_waitcnt lgkmcnt(0)
	v_mfma_f32_16x16x32_bf16 v[126:129], v[150:153], v[182:185], v[126:129]
	v_mfma_f32_16x16x32_bf16 v[126:129], v[154:157], v[186:189], v[126:129]
	v_mfma_f32_16x16x32_bf16 v[122:125], v[162:165], v[186:189], v[122:125]
	v_mfma_f32_16x16x32_bf16 v[122:125], v[158:161], v[182:185], v[122:125]
	v_mfma_f32_16x16x32_bf16 v[110:113], v[158:161], v[190:193], v[110:113]
	v_mfma_f32_16x16x32_bf16 v[110:113], v[162:165], v[194:197], v[110:113]
	v_mfma_f32_16x16x32_bf16 v[118:121], v[154:157], v[194:197], v[118:121]
	v_mfma_f32_16x16x32_bf16 v[118:121], v[150:153], v[190:193], v[118:121]
	v_mfma_f32_16x16x32_bf16 v[102:105], v[150:153], v[198:201], v[102:105]
	v_mfma_f32_16x16x32_bf16 v[102:105], v[154:157], v[202:205], v[102:105]
	v_mfma_f32_16x16x32_bf16 v[94:97], v[162:165], v[202:205], v[94:97]
	v_mfma_f32_16x16x32_bf16 v[94:97], v[158:161], v[198:201], v[94:97]
	v_mfma_f32_16x16x32_bf16 v[78:81], v[158:161], v[206:209], v[78:81]
	v_mfma_f32_16x16x32_bf16 v[78:81], v[162:165], v[210:213], v[78:81]
	v_mfma_f32_16x16x32_bf16 v[86:89], v[154:157], v[210:213], v[86:89]
	v_mfma_f32_16x16x32_bf16 v[86:89], v[150:153], v[206:209], v[86:89]
	s_setprio 0
	s_setprio 1
	v_mfma_f32_16x16x32_bf16 v[114:117], v[166:169], v[182:185], v[114:117]
	v_mfma_f32_16x16x32_bf16 v[114:117], v[170:173], v[186:189], v[114:117]
	v_mfma_f32_16x16x32_bf16 v[106:109], v[178:181], v[186:189], v[106:109]
	v_mfma_f32_16x16x32_bf16 v[106:109], v[174:177], v[182:185], v[106:109]
	v_mfma_f32_16x16x32_bf16 v[90:93], v[174:177], v[190:193], v[90:93]
	v_mfma_f32_16x16x32_bf16 v[90:93], v[178:181], v[194:197], v[90:93]
	v_mfma_f32_16x16x32_bf16 v[98:101], v[170:173], v[194:197], v[98:101]
	v_mfma_f32_16x16x32_bf16 v[98:101], v[166:169], v[190:193], v[98:101]
	v_mfma_f32_16x16x32_bf16 v[82:85], v[166:169], v[198:201], v[82:85]
	v_mfma_f32_16x16x32_bf16 v[82:85], v[170:173], v[202:205], v[82:85]
	v_mfma_f32_16x16x32_bf16 v[74:77], v[178:181], v[202:205], v[74:77]
	v_mfma_f32_16x16x32_bf16 v[74:77], v[174:177], v[198:201], v[74:77]
	v_mfma_f32_16x16x32_bf16 v[66:69], v[174:177], v[206:209], v[66:69]
	v_mfma_f32_16x16x32_bf16 v[66:69], v[178:181], v[210:213], v[66:69]
	v_mfma_f32_16x16x32_bf16 v[70:73], v[170:173], v[210:213], v[70:73]
	v_mfma_f32_16x16x32_bf16 v[70:73], v[166:169], v[206:209], v[70:73]
	s_setprio 0
	s_barrier
; #define PG8_STAGE(bufoff, gbase, voff) do { _Pragma("unroll") for (int _i = 0; _i < 2; ++_i) \
;         __builtin_amdgcn_global_load_lds((const unsigned*)((const char*)(gbase) + (voff)[_i]), (PG8_LAS unsigned*)(lds + (bufoff) + ldsw + _i * 8192), 16, 0, 0); } while (0)
; #define PG8_LDA(dst, b, h) do { _Pragma("unroll") for (int m = 0; m < 4; ++m) _Pragma("unroll") for (int k = 0; k < 2; ++k) dst[m][k] = *(const PG8_LAS bf16x8*)(lds + PG8_SA(b, h) + aoff + m * 2048 + k * 1024); } while (0)
; #define PG8_MMA(ai, bj, At, Bt) do { __builtin_amdgcn_s_setprio(1); _Pragma("unroll") for (int m = 0; m < 4; ++m) _Pragma("unroll") for (int n = 0; n < 2; ++n) _Pragma("unroll") for (int k = 0; k < 2; ++k) \
;         acc[ai][bj][m][n] = __builtin_amdgcn_mfma_f32_16x16x32_bf16(Bt[n][k], At[m][k], acc[ai][bj][m][n], 0, 0, 0); __builtin_amdgcn_s_setprio(0); } while (0)
; #define PG8_WAIT_V(n) asm volatile("s_waitcnt vmcnt(" #n ")" ::: "memory")
; #define PG8_WAIT_L(n) asm volatile("s_waitcnt lgkmcnt(" #n ")" ::: "memory")
; #define PG8_BAR __builtin_amdgcn_s_barrier()
; #define PG8_SCHED __builtin_amdgcn_sched_barrier(0)
; template <class Epi, class Sched, bool ALIGN_EPI>
; __device__ __forceinline__ void gemm_phase(PG8_LAS unsigned char* lds, const Gemm g, const Sched& S, const Epi& E) {
;     ...
;         for (int t = 0; t < nt; t += 2) {
;     ...
;             PG8_LDA(At, 1, 1); PG8_STAGE(PG8_SB(1, 0), b3, voffB); PG8_STAGE(PG8_SB(1, 1), b3 + hstepB, voffB); PG8_STAGE(PG8_SA(1, 0), a3, voffA);
;             PG8_WAIT_V(8); PG8_WAIT_L(0); PG8_BAR; PG8_MMA(1, 0, At, B0); PG8_MMA(1, 1, At, B1); PG8_BAR; PG8_SCHED;
	s_add_i32 s36, s55, s39
	v_lshl_add_u64 v[142:143], v[142:143], 0, s[8:9]
	s_mov_b32 m0, s36
	s_nop 0
	global_load_lds_dwordx4 v[142:143], off
	s_add_i32 m0, s36, 0x2000
	v_lshl_add_u64 v[142:143], v[214:215], 0, s[8:9]
	global_load_lds_dwordx4 v[142:143], off
	s_add_u32 s34, s34, 0x80080
	s_addc_u32 s35, s35, 0
	s_add_i32 s36, s56, s39
	v_lshl_add_u64 v[142:143], s[34:35], 0, v[132:133]
	s_mov_b32 m0, s36
	s_nop 0
	global_load_lds_dwordx4 v[142:143], off
	v_lshl_add_u64 v[142:143], s[34:35], 0, v[136:137]
	s_add_i32 m0, s36, 0x2000
	s_nop 0
	global_load_lds_dwordx4 v[142:143], off
	v_lshl_add_u64 v[142:143], v[216:217], 0, s[8:9]
	s_mov_b32 m0, s44
	s_nop 0
	global_load_lds_dwordx4 v[142:143], off
	v_lshl_add_u64 v[142:143], v[218:219], 0, s[8:9]
	s_mov_b32 m0, s45
	s_nop 0
	global_load_lds_dwordx4 v[142:143], off
	ds_read_b128 v[182:185], v149 offset:49152
	ds_read_b128 v[186:189], v149 offset:50176
	ds_read_b128 v[190:193], v149 offset:51200
	ds_read_b128 v[194:197], v149 offset:52224
	ds_read_b128 v[198:201], v149 offset:53248
	ds_read_b128 v[202:205], v149 offset:54272
	ds_read_b128 v[206:209], v149 offset:55296
	ds_read_b128 v[210:213], v149 offset:56320
	s_waitcnt vmcnt(8)
	s_waitcnt lgkmcnt(0)
	s_barrier
	s_setprio 1
	s_waitcnt lgkmcnt(0)
	v_mfma_f32_16x16x32_bf16 v[62:65], v[150:153], v[182:185], v[62:65]
	v_mfma_f32_16x16x32_bf16 v[62:65], v[154:157], v[186:189], v[62:65]
	v_mfma_f32_16x16x32_bf16 v[58:61], v[162:165], v[186:189], v[58:61]
	v_mfma_f32_16x16x32_bf16 v[58:61], v[158:161], v[182:185], v[58:61]
	v_mfma_f32_16x16x32_bf16 v[46:49], v[158:161], v[190:193], v[46:49]
	v_mfma_f32_16x16x32_bf16 v[46:49], v[162:165], v[194:197], v[46:49]
	v_mfma_f32_16x16x32_bf16 v[54:57], v[154:157], v[194:197], v[54:57]
	v_mfma_f32_16x16x32_bf16 v[54:57], v[150:153], v[190:193], v[54:57]
	v_mfma_f32_16x16x32_bf16 v[38:41], v[150:153], v[198:201], v[38:41]
	v_mfma_f32_16x16x32_bf16 v[38:41], v[154:157], v[202:205], v[38:41]
	v_mfma_f32_16x16x32_bf16 v[30:33], v[162:165], v[202:205], v[30:33]
	v_mfma_f32_16x16x32_bf16 v[30:33], v[158:161], v[198:201], v[30:33]
	v_mfma_f32_16x16x32_bf16 v[14:17], v[158:161], v[206:209], v[14:17]
	v_mfma_f32_16x16x32_bf16 v[14:17], v[162:165], v[210:213], v[14:17]
	v_mfma_f32_16x16x32_bf16 v[22:25], v[154:157], v[210:213], v[22:25]
	v_mfma_f32_16x16x32_bf16 v[22:25], v[150:153], v[206:209], v[22:25]
	s_setprio 0
	s_setprio 1
	v_mfma_f32_16x16x32_bf16 v[50:53], v[166:169], v[182:185], v[50:53]
	v_mfma_f32_16x16x32_bf16 v[50:53], v[170:173], v[186:189], v[50:53]
	v_mfma_f32_16x16x32_bf16 v[42:45], v[178:181], v[186:189], v[42:45]
	v_mfma_f32_16x16x32_bf16 v[42:45], v[174:177], v[182:185], v[42:45]
	v_mfma_f32_16x16x32_bf16 v[26:29], v[174:177], v[190:193], v[26:29]
	v_mfma_f32_16x16x32_bf16 v[26:29], v[178:181], v[194:197], v[26:29]
	v_mfma_f32_16x16x32_bf16 v[34:37], v[170:173], v[194:197], v[34:37]
	v_mfma_f32_16x16x32_bf16 v[34:37], v[166:169], v[190:193], v[34:37]
	v_mfma_f32_16x16x32_bf16 v[18:21], v[166:169], v[198:201], v[18:21]
	v_mfma_f32_16x16x32_bf16 v[18:21], v[170:173], v[202:205], v[18:21]
	v_mfma_f32_16x16x32_bf16 v[10:13], v[178:181], v[202:205], v[10:13]
	v_mfma_f32_16x16x32_bf16 v[10:13], v[174:177], v[198:201], v[10:13]
	v_mfma_f32_16x16x32_bf16 v[2:5], v[174:177], v[206:209], v[2:5]
	v_mfma_f32_16x16x32_bf16 v[2:5], v[178:181], v[210:213], v[2:5]
	v_mfma_f32_16x16x32_bf16 v[6:9], v[170:173], v[210:213], v[6:9]
	v_mfma_f32_16x16x32_bf16 v[6:9], v[166:169], v[206:209], v[6:9]
	s_setprio 0
	s_barrier
	s_add_i32 s54, s54, 2
	s_add_u32 s30, s30, 0x100
	s_addc_u32 s31, s31, 0
	s_add_u32 s21, s21, 0x100
	s_addc_u32 s23, s23, 0
	s_cmp_gt_u32 s54, 29
	s_cbranch_scc0 .LBB0_431
	s_and_b64 vcc, exec, s[10:11]
	s_cbranch_vccz .LBB0_434
	s_barrier

; #define PG8_STAGE(bufoff, gbase, voff) do { _Pragma("unroll") for (int _i = 0; _i < 2; ++_i) \
;         __builtin_amdgcn_global_load_lds((const unsigned*)((const char*)(gbase) + (voff)[_i]), (PG8_LAS unsigned*)(lds + (bufoff) + ldsw + _i * 8192), 16, 0, 0); } while (0)
; #define PG8_LDA(dst, b, h) do { _Pragma("unroll") for (int m = 0; m < 4; ++m) _Pragma("unroll") for (int k = 0; k < 2; ++k) dst[m][k] = *(const PG8_LAS bf16x8*)(lds + PG8_SA(b, h) + aoff + m * 2048 + k * 1024); } while (0)
; #define PG8_LDB(dst, b, h) do { _Pragma("unroll") for (int n = 0; n < 2; ++n) _Pragma("unroll") for (int k = 0; k < 2; ++k) dst[n][k] = *(const PG8_LAS bf16x8*)(lds + PG8_SB(b, h) + boff + n * 2048 + k * 1024); } while (0)
; #define PG8_MMA(ai, bj, At, Bt) do { __builtin_amdgcn_s_setprio(1); _Pragma("unroll") for (int m = 0; m < 4; ++m) _Pragma("unroll") for (int n = 0; n < 2; ++n) _Pragma("unroll") for (int k = 0; k < 2; ++k) \
;         acc[ai][bj][m][n] = __builtin_amdgcn_mfma_f32_16x16x32_bf16(Bt[n][k], At[m][k], acc[ai][bj][m][n], 0, 0, 0); __builtin_amdgcn_s_setprio(0); } while (0)
; #define PG8_WAIT_V(n) asm volatile("s_waitcnt vmcnt(" #n ")" ::: "memory")
; #define PG8_WAIT_L(n) asm volatile("s_waitcnt lgkmcnt(" #n ")" ::: "memory")
; #define PG8_BAR __builtin_amdgcn_s_barrier()
; #define PG8_SCHED __builtin_amdgcn_sched_barrier(0)
; template <class Epi, class Sched, bool ALIGN_EPI>
; __device__ __forceinline__ void gemm_phase(PG8_LAS unsigned char* lds, const Gemm g, const Sched& S, const Epi& E) {
;     ...
;             const char* a1 = cA + (size_t)(t + 1) * kstepA;
;             const char* a2 = last ? nA : cA + (size_t)(t + 2) * kstepA; const char* b2 = last ? nB : cB + (size_t)(t + 2) * kstep;
;             const char* a3 = a2 + kstepA; const char* b3 = b2 + kstep;
;             PG8_LDB(B0, 0, 0); PG8_LDB(B1, 0, 1); PG8_SCHED; PG8_LDA(At, 0, 0); PG8_STAGE(PG8_SA(1, 1), a1 + hstepA, voffA);
;             PG8_WAIT_V(8); PG8_WAIT_L(0); PG8_BAR; PG8_MMA(0, 0, At, B0); PG8_MMA(0, 1, At, B1); PG8_BAR; PG8_SCHED;
;             PG8_LDA(At, 0, 1); PG8_STAGE(PG8_SB(0, 0), b2, voffB); PG8_STAGE(PG8_SB(0, 1), b2 + hstepB, voffB); PG8_STAGE(PG8_SA(0, 0), a2, voffA);
;             PG8_WAIT_V(8); PG8_WAIT_L(0); PG8_BAR; PG8_MMA(1, 0, At, B0); PG8_MMA(1, 1, At, B1); PG8_BAR; PG8_SCHED;
.LBB0_778:
	s_add_u32 s36, s34, 0x400000
	s_addc_u32 s37, s35, 0
	s_cmp_eq_u32 s21, 12
	s_cselect_b32 s42, s24, s36
	s_cselect_b32 s43, s25, s37
	s_cselect_b32 s40, s26, s4
	s_cselect_b32 s41, s27, s5
	s_add_u32 s38, s42, 0x200000
	s_addc_u32 s39, s43, 0
	v_lshl_add_u64 v[222:223], s[34:35], 0, v[148:149]
	s_add_i32 m0, s31, 0xc000
	s_nop 0
	global_load_lds_dwordx4 v[222:223], off
	v_lshl_add_u64 v[222:223], s[34:35], 0, v[150:151]
	s_add_i32 m0, s31, 0xe000
	s_nop 0
	global_load_lds_dwordx4 v[222:223], off
	ds_read_b128 v[114:117], v178
	ds_read_b128 v[118:121], v178 offset:1024
	ds_read_b128 v[156:159], v178 offset:2048
	ds_read_b128 v[160:163], v178 offset:3072
	ds_read_b128 v[164:167], v179
	ds_read_b128 v[168:171], v179 offset:1024
	ds_read_b128 v[182:185], v179 offset:2048
	ds_read_b128 v[186:189], v179 offset:3072
	ds_read_b128 v[190:193], v180
	ds_read_b128 v[194:197], v180 offset:1024
	ds_read_b128 v[198:201], v180 offset:2048
	ds_read_b128 v[202:205], v180 offset:3072
	ds_read_b128 v[206:209], v180 offset:4096
	ds_read_b128 v[210:213], v180 offset:5120
	ds_read_b128 v[214:217], v180 offset:6144
	ds_read_b128 v[218:221], v180 offset:7168
	s_waitcnt vmcnt(8)
	s_waitcnt lgkmcnt(0)
	s_barrier
	s_setprio 1
	s_waitcnt lgkmcnt(0)
	v_mfma_f32_16x16x32_bf16 v[134:137], v[114:117], v[190:193], v[134:137]
	v_mfma_f32_16x16x32_bf16 v[134:137], v[118:121], v[194:197], v[134:137]
	v_mfma_f32_16x16x32_bf16 v[130:133], v[160:163], v[194:197], v[130:133]
	v_mfma_f32_16x16x32_bf16 v[130:133], v[156:159], v[190:193], v[130:133]
	v_mfma_f32_16x16x32_bf16 v[122:125], v[156:159], v[198:201], v[122:125]
	v_mfma_f32_16x16x32_bf16 v[122:125], v[160:163], v[202:205], v[122:125]
	v_mfma_f32_16x16x32_bf16 v[126:129], v[118:121], v[202:205], v[126:129]
	v_mfma_f32_16x16x32_bf16 v[126:129], v[114:117], v[198:201], v[126:129]
	v_mfma_f32_16x16x32_bf16 v[110:113], v[114:117], v[206:209], v[110:113]
	v_mfma_f32_16x16x32_bf16 v[110:113], v[118:121], v[210:213], v[110:113]
	v_mfma_f32_16x16x32_bf16 v[106:109], v[160:163], v[210:213], v[106:109]
	v_mfma_f32_16x16x32_bf16 v[106:109], v[156:159], v[206:209], v[106:109]
	v_mfma_f32_16x16x32_bf16 v[98:101], v[156:159], v[214:217], v[98:101]
	v_mfma_f32_16x16x32_bf16 v[98:101], v[160:163], v[218:221], v[98:101]
	v_mfma_f32_16x16x32_bf16 v[102:105], v[118:121], v[218:221], v[102:105]
	v_mfma_f32_16x16x32_bf16 v[102:105], v[114:117], v[214:217], v[102:105]
	s_setprio 0
	s_setprio 1
	v_mfma_f32_16x16x32_bf16 v[62:65], v[164:167], v[190:193], v[62:65]
	v_mfma_f32_16x16x32_bf16 v[62:65], v[168:171], v[194:197], v[62:65]
	v_mfma_f32_16x16x32_bf16 v[58:61], v[186:189], v[194:197], v[58:61]
	v_mfma_f32_16x16x32_bf16 v[58:61], v[182:185], v[190:193], v[58:61]
	v_mfma_f32_16x16x32_bf16 v[50:53], v[182:185], v[198:201], v[50:53]
	v_mfma_f32_16x16x32_bf16 v[50:53], v[186:189], v[202:205], v[50:53]
	v_mfma_f32_16x16x32_bf16 v[54:57], v[168:171], v[202:205], v[54:57]
	v_mfma_f32_16x16x32_bf16 v[54:57], v[164:167], v[198:201], v[54:57]
	v_mfma_f32_16x16x32_bf16 v[46:49], v[164:167], v[206:209], v[46:49]
	v_mfma_f32_16x16x32_bf16 v[46:49], v[168:171], v[210:213], v[46:49]
	v_mfma_f32_16x16x32_bf16 v[42:45], v[186:189], v[210:213], v[42:45]
	v_mfma_f32_16x16x32_bf16 v[42:45], v[182:185], v[206:209], v[42:45]
	v_mfma_f32_16x16x32_bf16 v[34:37], v[182:185], v[214:217], v[34:37]
	v_mfma_f32_16x16x32_bf16 v[34:37], v[186:189], v[218:221], v[34:37]
	v_mfma_f32_16x16x32_bf16 v[38:41], v[168:171], v[218:221], v[38:41]
	v_mfma_f32_16x16x32_bf16 v[38:41], v[164:167], v[214:217], v[38:41]
	s_setprio 0
	s_barrier
	s_add_i32 s2, s52, s3
	v_lshl_add_u64 v[222:223], s[40:41], 0, v[140:141]
	s_mov_b32 m0, s2
	s_nop 0
	global_load_lds_dwordx4 v[222:223], off
	s_add_i32 m0, s2, 0x2000
	v_lshl_add_u64 v[224:225], s[40:41], 0, v[144:145]
	global_load_lds_dwordx4 v[224:225], off
	s_add_u32 s34, s40, 0x40000
	s_addc_u32 s35, s41, 0
	s_add_i32 s2, s53, s3
	v_lshl_add_u64 v[226:227], s[34:35], 0, v[140:141]
	s_mov_b32 m0, s2
	s_nop 0
	global_load_lds_dwordx4 v[226:227], off
	v_lshl_add_u64 v[226:227], s[34:35], 0, v[144:145]
	s_add_i32 m0, s2, 0x2000
	s_nop 0
	global_load_lds_dwordx4 v[226:227], off
	v_lshl_add_u64 v[226:227], s[42:43], 0, v[138:139]
	s_mov_b32 m0, s31
	s_nop 0
	global_load_lds_dwordx4 v[226:227], off
	v_lshl_add_u64 v[226:227], s[42:43], 0, v[142:143]
	s_mov_b32 m0, s44
	s_nop 0
	global_load_lds_dwordx4 v[226:227], off
	ds_read_b128 v[190:193], v180 offset:16384
	ds_read_b128 v[194:197], v180 offset:17408
	ds_read_b128 v[198:201], v180 offset:18432
	ds_read_b128 v[202:205], v180 offset:19456
	ds_read_b128 v[206:209], v180 offset:20480
	ds_read_b128 v[210:213], v180 offset:21504
	ds_read_b128 v[214:217], v180 offset:22528
	ds_read_b128 v[218:221], v180 offset:23552
	s_waitcnt vmcnt(8)
	s_waitcnt lgkmcnt(0)
	s_barrier
; #define PG8_STAGE(bufoff, gbase, voff) do { _Pragma("unroll") for (int _i = 0; _i < 2; ++_i) \
;         __builtin_amdgcn_global_load_lds((const unsigned*)((const char*)(gbase) + (voff)[_i]), (PG8_LAS unsigned*)(lds + (bufoff) + ldsw + _i * 8192), 16, 0, 0); } while (0)
; #define PG8_LDA(dst, b, h) do { _Pragma("unroll") for (int m = 0; m < 4; ++m) _Pragma("unroll") for (int k = 0; k < 2; ++k) dst[m][k] = *(const PG8_LAS bf16x8*)(lds + PG8_SA(b, h) + aoff + m * 2048 + k * 1024); } while (0)
; #define PG8_LDB(dst, b, h) do { _Pragma("unroll") for (int n = 0; n < 2; ++n) _Pragma("unroll") for (int k = 0; k < 2; ++k) dst[n][k] = *(const PG8_LAS bf16x8*)(lds + PG8_SB(b, h) + boff + n * 2048 + k * 1024); } while (0)
; #define PG8_MMA(ai, bj, At, Bt) do { __builtin_amdgcn_s_setprio(1); _Pragma("unroll") for (int m = 0; m < 4; ++m) _Pragma("unroll") for (int n = 0; n < 2; ++n) _Pragma("unroll") for (int k = 0; k < 2; ++k) \
;         acc[ai][bj][m][n] = __builtin_amdgcn_mfma_f32_16x16x32_bf16(Bt[n][k], At[m][k], acc[ai][bj][m][n], 0, 0, 0); __builtin_amdgcn_s_setprio(0); } while (0)
; #define PG8_WAIT_V(n) asm volatile("s_waitcnt vmcnt(" #n ")" ::: "memory")
; #define PG8_WAIT_L(n) asm volatile("s_waitcnt lgkmcnt(" #n ")" ::: "memory")
; #define PG8_BAR __builtin_amdgcn_s_barrier()
; template <class Epi, class Sched, bool ALIGN_EPI>
; __device__ __forceinline__ void gemm_phase(PG8_LAS unsigned char* lds, const Gemm g, const Sched& S, const Epi& E) {
;     ...
;             PG8_WAIT_V(8); PG8_WAIT_L(0); PG8_BAR; PG8_MMA(0, 0, At, B0); PG8_MMA(0, 1, At, B1); PG8_BAR; PG8_SCHED;
;             PG8_LDA(At, 0, 1); PG8_STAGE(PG8_SB(0, 0), b2, voffB); PG8_STAGE(PG8_SB(0, 1), b2 + hstepB, voffB); PG8_STAGE(PG8_SA(0, 0), a2, voffA);
;             PG8_WAIT_V(8); PG8_WAIT_L(0); PG8_BAR; PG8_MMA(1, 0, At, B0); PG8_MMA(1, 1, At, B1); PG8_BAR; PG8_SCHED;
;             PG8_LDB(B0, 1, 0); PG8_LDB(B1, 1, 1); PG8_SCHED; PG8_LDA(At, 1, 0); PG8_STAGE(PG8_SA(0, 1), a2 + hstepA, voffA);
;             PG8_WAIT_V(8); PG8_WAIT_L(0); PG8_BAR; PG8_MMA(0, 0, At, B0); PG8_MMA(0, 1, At, B1); PG8_BAR; PG8_SCHED;
;             PG8_LDA(At, 1, 1); PG8_STAGE(PG8_SB(1, 0), b3, voffB); PG8_STAGE(PG8_SB(1, 1), b3 + hstepB, voffB); PG8_STAGE(PG8_SA(1, 0), a3, voffA);
;             PG8_WAIT_V(8); PG8_WAIT_L(0); PG8_BAR; PG8_MMA(1, 0, At, B0); PG8_MMA(1, 1, At, B1); PG8_BAR; PG8_SCHED;
	s_setprio 1
	s_waitcnt lgkmcnt(0)
	v_mfma_f32_16x16x32_bf16 v[94:97], v[114:117], v[190:193], v[94:97]
	v_mfma_f32_16x16x32_bf16 v[94:97], v[118:121], v[194:197], v[94:97]
	v_mfma_f32_16x16x32_bf16 v[90:93], v[160:163], v[194:197], v[90:93]
	v_mfma_f32_16x16x32_bf16 v[90:93], v[156:159], v[190:193], v[90:93]
	v_mfma_f32_16x16x32_bf16 v[82:85], v[156:159], v[198:201], v[82:85]
	v_mfma_f32_16x16x32_bf16 v[82:85], v[160:163], v[202:205], v[82:85]
	v_mfma_f32_16x16x32_bf16 v[86:89], v[118:121], v[202:205], v[86:89]
	v_mfma_f32_16x16x32_bf16 v[86:89], v[114:117], v[198:201], v[86:89]
	v_mfma_f32_16x16x32_bf16 v[78:81], v[114:117], v[206:209], v[78:81]
	v_mfma_f32_16x16x32_bf16 v[78:81], v[118:121], v[210:213], v[78:81]
	v_mfma_f32_16x16x32_bf16 v[74:77], v[160:163], v[210:213], v[74:77]
	v_mfma_f32_16x16x32_bf16 v[74:77], v[156:159], v[206:209], v[74:77]
	v_mfma_f32_16x16x32_bf16 v[66:69], v[156:159], v[214:217], v[66:69]
	v_mfma_f32_16x16x32_bf16 v[66:69], v[160:163], v[218:221], v[66:69]
	v_mfma_f32_16x16x32_bf16 v[70:73], v[118:121], v[218:221], v[70:73]
	v_mfma_f32_16x16x32_bf16 v[70:73], v[114:117], v[214:217], v[70:73]
	s_setprio 0
	s_setprio 1
	v_mfma_f32_16x16x32_bf16 v[30:33], v[164:167], v[190:193], v[30:33]
	v_mfma_f32_16x16x32_bf16 v[30:33], v[168:171], v[194:197], v[30:33]
	v_mfma_f32_16x16x32_bf16 v[26:29], v[186:189], v[194:197], v[26:29]
	v_mfma_f32_16x16x32_bf16 v[26:29], v[182:185], v[190:193], v[26:29]
	v_mfma_f32_16x16x32_bf16 v[18:21], v[182:185], v[198:201], v[18:21]
	v_mfma_f32_16x16x32_bf16 v[18:21], v[186:189], v[202:205], v[18:21]
	v_mfma_f32_16x16x32_bf16 v[22:25], v[168:171], v[202:205], v[22:25]
	v_mfma_f32_16x16x32_bf16 v[22:25], v[164:167], v[198:201], v[22:25]
	v_mfma_f32_16x16x32_bf16 v[14:17], v[164:167], v[206:209], v[14:17]
	v_mfma_f32_16x16x32_bf16 v[14:17], v[168:171], v[210:213], v[14:17]
	v_mfma_f32_16x16x32_bf16 v[10:13], v[186:189], v[210:213], v[10:13]
	v_mfma_f32_16x16x32_bf16 v[10:13], v[182:185], v[206:209], v[10:13]
	v_mfma_f32_16x16x32_bf16 v[2:5], v[182:185], v[214:217], v[2:5]
	v_mfma_f32_16x16x32_bf16 v[2:5], v[186:189], v[218:221], v[2:5]
	v_mfma_f32_16x16x32_bf16 v[6:9], v[168:171], v[218:221], v[6:9]
	v_mfma_f32_16x16x32_bf16 v[6:9], v[164:167], v[214:217], v[6:9]
	s_setprio 0
	s_barrier
	s_add_i32 s2, 0, 0x18000
	s_add_i32 s23, 0, 0x1c000
	s_add_u32 s34, s42, 0x1000
	s_addc_u32 s35, s43, 0
	s_mov_b32 m0, s45
	v_lshl_add_u64 v[226:227], s[34:35], 0, v[138:139]
	global_load_lds_dwordx4 v[226:227], off
	v_lshl_add_u64 v[226:227], s[34:35], 0, v[142:143]
	s_mov_b32 m0, s46
	s_nop 0
	global_load_lds_dwordx4 v[226:227], off
	v_add_u32_e32 v160, s2, v175
	ds_read_b128 v[114:117], v160
	ds_read_b128 v[118:121], v160 offset:1024
	ds_read_b128 v[156:159], v160 offset:2048
	ds_read_b128 v[160:163], v160 offset:3072
	v_add_u32_e32 v181, s23, v175
	ds_read_b128 v[164:167], v181
	ds_read_b128 v[168:171], v181 offset:1024
	ds_read_b128 v[182:185], v181 offset:2048
	ds_read_b128 v[186:189], v181 offset:3072
	ds_read_b128 v[190:193], v180 offset:32768
	ds_read_b128 v[194:197], v180 offset:33792
	ds_read_b128 v[198:201], v180 offset:34816
	ds_read_b128 v[202:205], v180 offset:35840
	ds_read_b128 v[206:209], v180 offset:36864
	ds_read_b128 v[210:213], v180 offset:37888
	ds_read_b128 v[214:217], v180 offset:38912
	ds_read_b128 v[218:221], v180 offset:39936
	s_waitcnt vmcnt(8)
	s_waitcnt lgkmcnt(0)
	s_barrier
	s_setprio 1
	s_waitcnt lgkmcnt(0)
	v_mfma_f32_16x16x32_bf16 v[134:137], v[114:117], v[190:193], v[134:137]
	v_mfma_f32_16x16x32_bf16 v[134:137], v[118:121], v[194:197], v[134:137]
	v_mfma_f32_16x16x32_bf16 v[130:133], v[160:163], v[194:197], v[130:133]
	v_mfma_f32_16x16x32_bf16 v[130:133], v[156:159], v[190:193], v[130:133]
	v_mfma_f32_16x16x32_bf16 v[122:125], v[156:159], v[198:201], v[122:125]
	v_mfma_f32_16x16x32_bf16 v[122:125], v[160:163], v[202:205], v[122:125]
	v_mfma_f32_16x16x32_bf16 v[126:129], v[118:121], v[202:205], v[126:129]
	v_mfma_f32_16x16x32_bf16 v[126:129], v[114:117], v[198:201], v[126:129]
	v_mfma_f32_16x16x32_bf16 v[110:113], v[114:117], v[206:209], v[110:113]
	v_mfma_f32_16x16x32_bf16 v[110:113], v[118:121], v[210:213], v[110:113]
	v_mfma_f32_16x16x32_bf16 v[106:109], v[160:163], v[210:213], v[106:109]
	v_mfma_f32_16x16x32_bf16 v[106:109], v[156:159], v[206:209], v[106:109]
	v_mfma_f32_16x16x32_bf16 v[98:101], v[156:159], v[214:217], v[98:101]
	v_mfma_f32_16x16x32_bf16 v[98:101], v[160:163], v[218:221], v[98:101]
	v_mfma_f32_16x16x32_bf16 v[102:105], v[118:121], v[218:221], v[102:105]
	v_mfma_f32_16x16x32_bf16 v[102:105], v[114:117], v[214:217], v[102:105]
	s_setprio 0
	s_setprio 1
	v_mfma_f32_16x16x32_bf16 v[62:65], v[164:167], v[190:193], v[62:65]
	v_mfma_f32_16x16x32_bf16 v[62:65], v[168:171], v[194:197], v[62:65]
	v_mfma_f32_16x16x32_bf16 v[58:61], v[186:189], v[194:197], v[58:61]
	v_mfma_f32_16x16x32_bf16 v[58:61], v[182:185], v[190:193], v[58:61]
	v_mfma_f32_16x16x32_bf16 v[50:53], v[182:185], v[198:201], v[50:53]
	v_mfma_f32_16x16x32_bf16 v[50:53], v[186:189], v[202:205], v[50:53]
	v_mfma_f32_16x16x32_bf16 v[54:57], v[168:171], v[202:205], v[54:57]
	v_mfma_f32_16x16x32_bf16 v[54:57], v[164:167], v[198:201], v[54:57]
	v_mfma_f32_16x16x32_bf16 v[46:49], v[164:167], v[206:209], v[46:49]
	v_mfma_f32_16x16x32_bf16 v[46:49], v[168:171], v[210:213], v[46:49]
	v_mfma_f32_16x16x32_bf16 v[42:45], v[186:189], v[210:213], v[42:45]
	v_mfma_f32_16x16x32_bf16 v[42:45], v[182:185], v[206:209], v[42:45]
	v_mfma_f32_16x16x32_bf16 v[34:37], v[182:185], v[214:217], v[34:37]
	v_mfma_f32_16x16x32_bf16 v[34:37], v[186:189], v[218:221], v[34:37]
	v_mfma_f32_16x16x32_bf16 v[38:41], v[168:171], v[218:221], v[38:41]
	v_mfma_f32_16x16x32_bf16 v[38:41], v[164:167], v[214:217], v[38:41]
	s_setprio 0
	s_barrier
; #define PG8_STAGE(bufoff, gbase, voff) do { _Pragma("unroll") for (int _i = 0; _i < 2; ++_i) \
;         __builtin_amdgcn_global_load_lds((const unsigned*)((const char*)(gbase) + (voff)[_i]), (PG8_LAS unsigned*)(lds + (bufoff) + ldsw + _i * 8192), 16, 0, 0); } while (0)
; #define PG8_LDA(dst, b, h) do { _Pragma("unroll") for (int m = 0; m < 4; ++m) _Pragma("unroll") for (int k = 0; k < 2; ++k) dst[m][k] = *(const PG8_LAS bf16x8*)(lds + PG8_SA(b, h) + aoff + m * 2048 + k * 1024); } while (0)
; #define PG8_MMA(ai, bj, At, Bt) do { __builtin_amdgcn_s_setprio(1); _Pragma("unroll") for (int m = 0; m < 4; ++m) _Pragma("unroll") for (int n = 0; n < 2; ++n) _Pragma("unroll") for (int k = 0; k < 2; ++k) \
;         acc[ai][bj][m][n] = __builtin_amdgcn_mfma_f32_16x16x32_bf16(Bt[n][k], At[m][k], acc[ai][bj][m][n], 0, 0, 0); __builtin_amdgcn_s_setprio(0); } while (0)
; #define PG8_WAIT_V(n) asm volatile("s_waitcnt vmcnt(" #n ")" ::: "memory")
; #define PG8_WAIT_L(n) asm volatile("s_waitcnt lgkmcnt(" #n ")" ::: "memory")
; #define PG8_BAR __builtin_amdgcn_s_barrier()
; #define PG8_SCHED __builtin_amdgcn_sched_barrier(0)
; template <class Epi, class Sched, bool ALIGN_EPI>
; __device__ __forceinline__ void gemm_phase(PG8_LAS unsigned char* lds, const Gemm g, const Sched& S, const Epi& E) {
;     ...
;         for (int t = 0; t < nt; t += 2) {
;     ...
;             PG8_LDA(At, 1, 1); PG8_STAGE(PG8_SB(1, 0), b3, voffB); PG8_STAGE(PG8_SB(1, 1), b3 + hstepB, voffB); PG8_STAGE(PG8_SA(1, 0), a3, voffA);
;             PG8_WAIT_V(8); PG8_WAIT_L(0); PG8_BAR; PG8_MMA(1, 0, At, B0); PG8_MMA(1, 1, At, B1); PG8_BAR; PG8_SCHED;
	s_add_i32 s2, s2, s3
	v_lshl_add_u64 v[222:223], v[222:223], 0, s[16:17]
	s_mov_b32 m0, s2
	s_nop 0
	global_load_lds_dwordx4 v[222:223], off
	s_add_i32 m0, s2, 0x2000
	v_lshl_add_u64 v[222:223], v[224:225], 0, s[16:17]
	global_load_lds_dwordx4 v[222:223], off
	s_add_u32 s34, s40, 0x40080
	s_addc_u32 s35, s41, 0
	s_add_i32 s2, s23, s3
	v_lshl_add_u64 v[222:223], s[34:35], 0, v[140:141]
	s_mov_b32 m0, s2
	s_nop 0
	global_load_lds_dwordx4 v[222:223], off
	v_lshl_add_u64 v[222:223], s[34:35], 0, v[144:145]
	s_add_i32 m0, s2, 0x2000
	s_nop 0
	global_load_lds_dwordx4 v[222:223], off
	v_lshl_add_u64 v[222:223], s[38:39], 0, v[138:139]
	s_mov_b32 m0, s48
	s_nop 0
	global_load_lds_dwordx4 v[222:223], off
	v_lshl_add_u64 v[222:223], s[38:39], 0, v[142:143]
	s_mov_b32 m0, s49
	s_nop 0
	global_load_lds_dwordx4 v[222:223], off
	ds_read_b128 v[190:193], v180 offset:49152
	ds_read_b128 v[194:197], v180 offset:50176
	ds_read_b128 v[198:201], v180 offset:51200
	ds_read_b128 v[202:205], v180 offset:52224
	ds_read_b128 v[206:209], v180 offset:53248
	ds_read_b128 v[210:213], v180 offset:54272
	ds_read_b128 v[214:217], v180 offset:55296
	ds_read_b128 v[218:221], v180 offset:56320
	s_waitcnt vmcnt(8)
	s_waitcnt lgkmcnt(0)
	s_barrier
	s_setprio 1
	s_waitcnt lgkmcnt(0)
	v_mfma_f32_16x16x32_bf16 v[94:97], v[114:117], v[190:193], v[94:97]
	v_mfma_f32_16x16x32_bf16 v[94:97], v[118:121], v[194:197], v[94:97]
	v_mfma_f32_16x16x32_bf16 v[90:93], v[160:163], v[194:197], v[90:93]
	v_mfma_f32_16x16x32_bf16 v[90:93], v[156:159], v[190:193], v[90:93]
	v_mfma_f32_16x16x32_bf16 v[82:85], v[156:159], v[198:201], v[82:85]
	v_mfma_f32_16x16x32_bf16 v[82:85], v[160:163], v[202:205], v[82:85]
	v_mfma_f32_16x16x32_bf16 v[86:89], v[118:121], v[202:205], v[86:89]
	v_mfma_f32_16x16x32_bf16 v[86:89], v[114:117], v[198:201], v[86:89]
	v_mfma_f32_16x16x32_bf16 v[78:81], v[114:117], v[206:209], v[78:81]
	v_mfma_f32_16x16x32_bf16 v[78:81], v[118:121], v[210:213], v[78:81]
	v_mfma_f32_16x16x32_bf16 v[74:77], v[160:163], v[210:213], v[74:77]
	v_mfma_f32_16x16x32_bf16 v[74:77], v[156:159], v[206:209], v[74:77]
	v_mfma_f32_16x16x32_bf16 v[66:69], v[156:159], v[214:217], v[66:69]
	v_mfma_f32_16x16x32_bf16 v[66:69], v[160:163], v[218:221], v[66:69]
	v_mfma_f32_16x16x32_bf16 v[70:73], v[118:121], v[218:221], v[70:73]
	v_mfma_f32_16x16x32_bf16 v[70:73], v[114:117], v[214:217], v[70:73]
	s_setprio 0
	s_setprio 1
	v_mfma_f32_16x16x32_bf16 v[30:33], v[164:167], v[190:193], v[30:33]
	v_mfma_f32_16x16x32_bf16 v[30:33], v[168:171], v[194:197], v[30:33]
	v_mfma_f32_16x16x32_bf16 v[26:29], v[186:189], v[194:197], v[26:29]
	v_mfma_f32_16x16x32_bf16 v[26:29], v[182:185], v[190:193], v[26:29]
	v_mfma_f32_16x16x32_bf16 v[18:21], v[182:185], v[198:201], v[18:21]
	v_mfma_f32_16x16x32_bf16 v[18:21], v[186:189], v[202:205], v[18:21]
	v_mfma_f32_16x16x32_bf16 v[22:25], v[168:171], v[202:205], v[22:25]
	v_mfma_f32_16x16x32_bf16 v[22:25], v[164:167], v[198:201], v[22:25]
	v_mfma_f32_16x16x32_bf16 v[14:17], v[164:167], v[206:209], v[14:17]
	v_mfma_f32_16x16x32_bf16 v[14:17], v[168:171], v[210:213], v[14:17]
	v_mfma_f32_16x16x32_bf16 v[10:13], v[186:189], v[210:213], v[10:13]
	v_mfma_f32_16x16x32_bf16 v[10:13], v[182:185], v[206:209], v[10:13]
	v_mfma_f32_16x16x32_bf16 v[2:5], v[182:185], v[214:217], v[2:5]
	v_mfma_f32_16x16x32_bf16 v[2:5], v[186:189], v[218:221], v[2:5]
	v_mfma_f32_16x16x32_bf16 v[6:9], v[168:171], v[218:221], v[6:9]
	v_mfma_f32_16x16x32_bf16 v[6:9], v[164:167], v[214:217], v[6:9]
	s_setprio 0
	s_barrier
	s_add_i32 s21, s21, 2
	s_add_u32 s4, s4, 0x100
	s_addc_u32 s5, s5, 0
	s_cmp_gt_u32 s21, 13
	s_mov_b64 s[34:35], s[36:37]
	s_cbranch_scc0 .LBB0_778
	s_and_b64 vcc, exec, s[18:19]
	s_cbranch_vccz .LBB0_781
	s_barrier

; #define PG8_STAGE(bufoff, gbase, voff) do { _Pragma("unroll") for (int _i = 0; _i < 2; ++_i) \
;         __builtin_amdgcn_global_load_lds((const unsigned*)((const char*)(gbase) + (voff)[_i]), (PG8_LAS unsigned*)(lds + (bufoff) + ldsw + _i * 8192), 16, 0, 0); } while (0)
; #define PG8_LDA(dst, b, h) do { _Pragma("unroll") for (int m = 0; m < 4; ++m) _Pragma("unroll") for (int k = 0; k < 2; ++k) dst[m][k] = *(const PG8_LAS bf16x8*)(lds + PG8_SA(b, h) + aoff + m * 2048 + k * 1024); } while (0)
; #define PG8_LDB(dst, b, h) do { _Pragma("unroll") for (int n = 0; n < 2; ++n) _Pragma("unroll") for (int k = 0; k < 2; ++k) dst[n][k] = *(const PG8_LAS bf16x8*)(lds + PG8_SB(b, h) + boff + n * 2048 + k * 1024); } while (0)
; #define PG8_MMA(ai, bj, At, Bt) do { __builtin_amdgcn_s_setprio(1); _Pragma("unroll") for (int m = 0; m < 4; ++m) _Pragma("unroll") for (int n = 0; n < 2; ++n) _Pragma("unroll") for (int k = 0; k < 2; ++k) \
;         acc[ai][bj][m][n] = __builtin_amdgcn_mfma_f32_16x16x32_bf16(Bt[n][k], At[m][k], acc[ai][bj][m][n], 0, 0, 0); __builtin_amdgcn_s_setprio(0); } while (0)
; #define PG8_WAIT_V(n) asm volatile("s_waitcnt vmcnt(" #n ")" ::: "memory")
; #define PG8_WAIT_L(n) asm volatile("s_waitcnt lgkmcnt(" #n ")" ::: "memory")
; #define PG8_BAR __builtin_amdgcn_s_barrier()
; #define PG8_SCHED __builtin_amdgcn_sched_barrier(0)
; template <class Epi, class Sched, bool ALIGN_EPI>
; __device__ __forceinline__ void gemm_phase(PG8_LAS unsigned char* lds, const Gemm g, const Sched& S, const Epi& E) {
;     ...
;             const char* a1 = cA + (size_t)(t + 1) * kstepA;
;             const char* a2 = last ? nA : cA + (size_t)(t + 2) * kstepA; const char* b2 = last ? nB : cB + (size_t)(t + 2) * kstep;
;             const char* a3 = a2 + kstepA; const char* b3 = b2 + kstep;
;             PG8_LDB(B0, 0, 0); PG8_LDB(B1, 0, 1); PG8_SCHED; PG8_LDA(At, 0, 0); PG8_STAGE(PG8_SA(1, 1), a1 + hstepA, voffA);
;             PG8_WAIT_V(8); PG8_WAIT_L(0); PG8_BAR; PG8_MMA(0, 0, At, B0); PG8_MMA(0, 1, At, B1); PG8_BAR; PG8_SCHED;
;             PG8_LDA(At, 0, 1); PG8_STAGE(PG8_SB(0, 0), b2, voffB); PG8_STAGE(PG8_SB(0, 1), b2 + hstepB, voffB); PG8_STAGE(PG8_SA(0, 0), a2, voffA);
;             PG8_WAIT_V(8); PG8_WAIT_L(0); PG8_BAR; PG8_MMA(1, 0, At, B0); PG8_MMA(1, 1, At, B1); PG8_BAR; PG8_SCHED;
.LBB0_839:
	s_add_u32 s2, s38, s40
	s_addc_u32 s42, s39, s41
	s_add_u32 s2, s2, 0x100
	s_addc_u32 s42, s42, 0
	s_add_u32 s63, s27, s40
	s_addc_u32 s43, s29, s41
	s_cmpk_eq_i32 s40, 0xf00
	s_cselect_b32 s45, s31, s42
	s_cselect_b32 s44, s30, s2
	s_cselect_b32 s43, s35, s43
	s_cselect_b32 s42, s34, s63
	v_lshl_add_u64 v[4:5], v[150:151], 0, s[40:41]
	s_add_i32 m0, s37, 0xc000
	s_nop 0
	global_load_lds_dwordx4 v[4:5], off
	v_lshl_add_u64 v[4:5], v[152:153], 0, s[40:41]
	s_add_i32 m0, s37, 0xe000
	s_nop 0
	global_load_lds_dwordx4 v[4:5], off
	v_add_u32_e32 v3, s55, v155
	ds_read_b128 v[160:163], v3
	ds_read_b128 v[164:167], v3 offset:1024
	ds_read_b128 v[168:171], v3 offset:2048
	ds_read_b128 v[174:177], v3 offset:3072
	v_add_u32_e32 v3, s56, v155
	ds_read_b128 v[178:181], v3
	ds_read_b128 v[182:185], v3 offset:1024
	ds_read_b128 v[186:189], v3 offset:2048
	ds_read_b128 v[190:193], v3 offset:3072
	ds_read_b128 v[194:197], v159
	ds_read_b128 v[198:201], v159 offset:1024
	ds_read_b128 v[202:205], v159 offset:2048
	ds_read_b128 v[206:209], v159 offset:3072
	ds_read_b128 v[210:213], v159 offset:4096
	ds_read_b128 v[214:217], v159 offset:5120
	ds_read_b128 v[218:221], v159 offset:6144
	ds_read_b128 v[222:225], v159 offset:7168
	s_waitcnt vmcnt(8)
	s_waitcnt lgkmcnt(0)
	s_barrier
	s_setprio 1
	s_waitcnt lgkmcnt(0)
	v_mfma_f32_16x16x32_bf16 v[130:133], v[160:163], v[194:197], v[130:133]
	v_mfma_f32_16x16x32_bf16 v[130:133], v[164:167], v[198:201], v[130:133]
	v_mfma_f32_16x16x32_bf16 v[126:129], v[174:177], v[198:201], v[126:129]
	v_mfma_f32_16x16x32_bf16 v[126:129], v[168:171], v[194:197], v[126:129]
	v_mfma_f32_16x16x32_bf16 v[110:113], v[168:171], v[202:205], v[110:113]
	v_mfma_f32_16x16x32_bf16 v[110:113], v[174:177], v[206:209], v[110:113]
	v_mfma_f32_16x16x32_bf16 v[114:117], v[164:167], v[206:209], v[114:117]
	v_mfma_f32_16x16x32_bf16 v[114:117], v[160:163], v[202:205], v[114:117]
	v_mfma_f32_16x16x32_bf16 v[98:101], v[160:163], v[210:213], v[98:101]
	v_mfma_f32_16x16x32_bf16 v[98:101], v[164:167], v[214:217], v[98:101]
	v_mfma_f32_16x16x32_bf16 v[94:97], v[174:177], v[214:217], v[94:97]
	v_mfma_f32_16x16x32_bf16 v[94:97], v[168:171], v[210:213], v[94:97]
	v_mfma_f32_16x16x32_bf16 v[78:81], v[168:171], v[218:221], v[78:81]
	v_mfma_f32_16x16x32_bf16 v[78:81], v[174:177], v[222:225], v[78:81]
	v_mfma_f32_16x16x32_bf16 v[82:85], v[164:167], v[222:225], v[82:85]
	v_mfma_f32_16x16x32_bf16 v[82:85], v[160:163], v[218:221], v[82:85]
	s_setprio 0
	s_setprio 1
	v_mfma_f32_16x16x32_bf16 v[122:125], v[178:181], v[194:197], v[122:125]
	v_mfma_f32_16x16x32_bf16 v[122:125], v[182:185], v[198:201], v[122:125]
	v_mfma_f32_16x16x32_bf16 v[118:121], v[190:193], v[198:201], v[118:121]
	v_mfma_f32_16x16x32_bf16 v[118:121], v[186:189], v[194:197], v[118:121]
	v_mfma_f32_16x16x32_bf16 v[102:105], v[186:189], v[202:205], v[102:105]
	v_mfma_f32_16x16x32_bf16 v[102:105], v[190:193], v[206:209], v[102:105]
	v_mfma_f32_16x16x32_bf16 v[106:109], v[182:185], v[206:209], v[106:109]
	v_mfma_f32_16x16x32_bf16 v[106:109], v[178:181], v[202:205], v[106:109]
	v_mfma_f32_16x16x32_bf16 v[90:93], v[178:181], v[210:213], v[90:93]
	v_mfma_f32_16x16x32_bf16 v[90:93], v[182:185], v[214:217], v[90:93]
	v_mfma_f32_16x16x32_bf16 v[86:89], v[190:193], v[214:217], v[86:89]
	v_mfma_f32_16x16x32_bf16 v[86:89], v[186:189], v[210:213], v[86:89]
	v_mfma_f32_16x16x32_bf16 v[70:73], v[186:189], v[218:221], v[70:73]
	v_mfma_f32_16x16x32_bf16 v[70:73], v[190:193], v[222:225], v[70:73]
	v_mfma_f32_16x16x32_bf16 v[74:77], v[182:185], v[222:225], v[74:77]
	v_mfma_f32_16x16x32_bf16 v[74:77], v[178:181], v[218:221], v[74:77]
	s_setprio 0
	s_barrier
	s_add_i32 s2, s55, s4
	v_lshl_add_u64 v[226:227], s[42:43], 0, v[136:137]
	s_mov_b32 m0, s2
	s_nop 0
	global_load_lds_dwordx4 v[226:227], off
	s_add_i32 m0, s2, 0x2000
	v_lshl_add_u64 v[228:229], s[42:43], 0, v[140:141]
	global_load_lds_dwordx4 v[228:229], off
	s_add_u32 s64, s42, 0x80000
	s_addc_u32 s65, s43, 0
	s_add_i32 s2, s56, s4
	v_lshl_add_u64 v[4:5], s[64:65], 0, v[136:137]
	s_mov_b32 m0, s2
	s_nop 0
	global_load_lds_dwordx4 v[4:5], off
	v_lshl_add_u64 v[4:5], s[64:65], 0, v[140:141]
	s_add_i32 m0, s2, 0x2000
	s_nop 0
	global_load_lds_dwordx4 v[4:5], off
	v_lshl_add_u64 v[230:231], s[44:45], 0, v[134:135]
	s_mov_b32 m0, s37
	s_nop 0
	global_load_lds_dwordx4 v[230:231], off
	v_lshl_add_u64 v[232:233], s[44:45], 0, v[138:139]
	s_mov_b32 m0, s48
	s_nop 0
	global_load_lds_dwordx4 v[232:233], off
	ds_read_b128 v[194:197], v159 offset:16384
	ds_read_b128 v[198:201], v159 offset:17408
	ds_read_b128 v[202:205], v159 offset:18432
	ds_read_b128 v[206:209], v159 offset:19456
	ds_read_b128 v[210:213], v159 offset:20480
	ds_read_b128 v[214:217], v159 offset:21504
	ds_read_b128 v[218:221], v159 offset:22528
	ds_read_b128 v[222:225], v159 offset:23552
	s_waitcnt vmcnt(8)
	s_waitcnt lgkmcnt(0)
	s_barrier
; #define PG8_STAGE(bufoff, gbase, voff) do { _Pragma("unroll") for (int _i = 0; _i < 2; ++_i) \
;         __builtin_amdgcn_global_load_lds((const unsigned*)((const char*)(gbase) + (voff)[_i]), (PG8_LAS unsigned*)(lds + (bufoff) + ldsw + _i * 8192), 16, 0, 0); } while (0)
; #define PG8_LDA(dst, b, h) do { _Pragma("unroll") for (int m = 0; m < 4; ++m) _Pragma("unroll") for (int k = 0; k < 2; ++k) dst[m][k] = *(const PG8_LAS bf16x8*)(lds + PG8_SA(b, h) + aoff + m * 2048 + k * 1024); } while (0)
; #define PG8_LDB(dst, b, h) do { _Pragma("unroll") for (int n = 0; n < 2; ++n) _Pragma("unroll") for (int k = 0; k < 2; ++k) dst[n][k] = *(const PG8_LAS bf16x8*)(lds + PG8_SB(b, h) + boff + n * 2048 + k * 1024); } while (0)
; #define PG8_MMA(ai, bj, At, Bt) do { __builtin_amdgcn_s_setprio(1); _Pragma("unroll") for (int m = 0; m < 4; ++m) _Pragma("unroll") for (int n = 0; n < 2; ++n) _Pragma("unroll") for (int k = 0; k < 2; ++k) \
;         acc[ai][bj][m][n] = __builtin_amdgcn_mfma_f32_16x16x32_bf16(Bt[n][k], At[m][k], acc[ai][bj][m][n], 0, 0, 0); __builtin_amdgcn_s_setprio(0); } while (0)
; #define PG8_WAIT_V(n) asm volatile("s_waitcnt vmcnt(" #n ")" ::: "memory")
; #define PG8_WAIT_L(n) asm volatile("s_waitcnt lgkmcnt(" #n ")" ::: "memory")
; #define PG8_BAR __builtin_amdgcn_s_barrier()
; template <class Epi, class Sched, bool ALIGN_EPI>
; __device__ __forceinline__ void gemm_phase(PG8_LAS unsigned char* lds, const Gemm g, const Sched& S, const Epi& E) {
;     ...
;             PG8_WAIT_V(8); PG8_WAIT_L(0); PG8_BAR; PG8_MMA(0, 0, At, B0); PG8_MMA(0, 1, At, B1); PG8_BAR; PG8_SCHED;
;             PG8_LDA(At, 0, 1); PG8_STAGE(PG8_SB(0, 0), b2, voffB); PG8_STAGE(PG8_SB(0, 1), b2 + hstepB, voffB); PG8_STAGE(PG8_SA(0, 0), a2, voffA);
;             PG8_WAIT_V(8); PG8_WAIT_L(0); PG8_BAR; PG8_MMA(1, 0, At, B0); PG8_MMA(1, 1, At, B1); PG8_BAR; PG8_SCHED;
;             PG8_LDB(B0, 1, 0); PG8_LDB(B1, 1, 1); PG8_SCHED; PG8_LDA(At, 1, 0); PG8_STAGE(PG8_SA(0, 1), a2 + hstepA, voffA);
;             PG8_WAIT_V(8); PG8_WAIT_L(0); PG8_BAR; PG8_MMA(0, 0, At, B0); PG8_MMA(0, 1, At, B1); PG8_BAR; PG8_SCHED;
;             PG8_LDA(At, 1, 1); PG8_STAGE(PG8_SB(1, 0), b3, voffB); PG8_STAGE(PG8_SB(1, 1), b3 + hstepB, voffB); PG8_STAGE(PG8_SA(1, 0), a3, voffA);
;             PG8_WAIT_V(8); PG8_WAIT_L(0); PG8_BAR; PG8_MMA(1, 0, At, B0); PG8_MMA(1, 1, At, B1); PG8_BAR; PG8_SCHED;
	s_setprio 1
	s_waitcnt lgkmcnt(0)
	v_mfma_f32_16x16x32_bf16 v[66:69], v[160:163], v[194:197], v[66:69]
	v_mfma_f32_16x16x32_bf16 v[66:69], v[164:167], v[198:201], v[66:69]
	v_mfma_f32_16x16x32_bf16 v[62:65], v[174:177], v[198:201], v[62:65]
	v_mfma_f32_16x16x32_bf16 v[62:65], v[168:171], v[194:197], v[62:65]
	v_mfma_f32_16x16x32_bf16 v[46:49], v[168:171], v[202:205], v[46:49]
	v_mfma_f32_16x16x32_bf16 v[46:49], v[174:177], v[206:209], v[46:49]
	v_mfma_f32_16x16x32_bf16 v[50:53], v[164:167], v[206:209], v[50:53]
	v_mfma_f32_16x16x32_bf16 v[50:53], v[160:163], v[202:205], v[50:53]
	v_mfma_f32_16x16x32_bf16 v[34:37], v[160:163], v[210:213], v[34:37]
	v_mfma_f32_16x16x32_bf16 v[34:37], v[164:167], v[214:217], v[34:37]
	v_mfma_f32_16x16x32_bf16 v[30:33], v[174:177], v[214:217], v[30:33]
	v_mfma_f32_16x16x32_bf16 v[30:33], v[168:171], v[210:213], v[30:33]
	v_mfma_f32_16x16x32_bf16 v[14:17], v[168:171], v[218:221], v[14:17]
	v_mfma_f32_16x16x32_bf16 v[14:17], v[174:177], v[222:225], v[14:17]
	v_mfma_f32_16x16x32_bf16 v[18:21], v[164:167], v[222:225], v[18:21]
	v_mfma_f32_16x16x32_bf16 v[18:21], v[160:163], v[218:221], v[18:21]
	s_setprio 0
	s_setprio 1
	v_mfma_f32_16x16x32_bf16 v[58:61], v[178:181], v[194:197], v[58:61]
	v_mfma_f32_16x16x32_bf16 v[54:57], v[186:189], v[194:197], v[54:57]
	v_mfma_f32_16x16x32_bf16 v[42:45], v[178:181], v[202:205], v[42:45]
	v_mfma_f32_16x16x32_bf16 v[38:41], v[186:189], v[202:205], v[38:41]
	v_mfma_f32_16x16x32_bf16 v[26:29], v[178:181], v[210:213], v[26:29]
	v_mfma_f32_16x16x32_bf16 v[22:25], v[186:189], v[210:213], v[22:25]
	v_mfma_f32_16x16x32_bf16 v[10:13], v[178:181], v[218:221], v[10:13]
	v_mfma_f32_16x16x32_bf16 v[4:7], v[186:189], v[218:221], v[6:9]
	v_mfma_f32_16x16x32_bf16 v[58:61], v[182:185], v[198:201], v[58:61]
	v_mfma_f32_16x16x32_bf16 v[54:57], v[190:193], v[198:201], v[54:57]
	v_mfma_f32_16x16x32_bf16 v[42:45], v[182:185], v[206:209], v[42:45]
	v_mfma_f32_16x16x32_bf16 v[38:41], v[190:193], v[206:209], v[38:41]
	v_mfma_f32_16x16x32_bf16 v[26:29], v[182:185], v[214:217], v[26:29]
	v_mfma_f32_16x16x32_bf16 v[22:25], v[190:193], v[214:217], v[22:25]
	v_mfma_f32_16x16x32_bf16 v[10:13], v[182:185], v[222:225], v[10:13]
	v_mfma_f32_16x16x32_bf16 v[4:7], v[190:193], v[222:225], v[4:7]
	s_setprio 0
	s_barrier
	s_add_i32 s2, 0, 0x18000
	s_add_i32 s63, 0, 0x1c000
	s_add_u32 s44, s44, 0x80000
	s_addc_u32 s45, s45, 0
	s_mov_b32 m0, s49
	v_lshl_add_u64 v[8:9], s[44:45], 0, v[134:135]
	global_load_lds_dwordx4 v[8:9], off
	v_lshl_add_u64 v[8:9], s[44:45], 0, v[138:139]
	s_mov_b32 m0, s50
	s_nop 0
	global_load_lds_dwordx4 v[8:9], off
	v_add_u32_e32 v3, s2, v155
	ds_read_b128 v[160:163], v3
	ds_read_b128 v[164:167], v3 offset:1024
	ds_read_b128 v[168:171], v3 offset:2048
	ds_read_b128 v[174:177], v3 offset:3072
	v_add_u32_e32 v3, s63, v155
	ds_read_b128 v[178:181], v3
	ds_read_b128 v[182:185], v3 offset:1024
	ds_read_b128 v[186:189], v3 offset:2048
	ds_read_b128 v[190:193], v3 offset:3072
	ds_read_b128 v[194:197], v159 offset:32768
	ds_read_b128 v[198:201], v159 offset:33792
	ds_read_b128 v[202:205], v159 offset:34816
	ds_read_b128 v[206:209], v159 offset:35840
	ds_read_b128 v[210:213], v159 offset:36864
	ds_read_b128 v[214:217], v159 offset:37888
	ds_read_b128 v[218:221], v159 offset:38912
	ds_read_b128 v[222:225], v159 offset:39936
	s_waitcnt vmcnt(8)
	s_waitcnt lgkmcnt(0)
	s_barrier
	s_setprio 1
	s_waitcnt lgkmcnt(0)
	v_mfma_f32_16x16x32_bf16 v[130:133], v[160:163], v[194:197], v[130:133]
	v_mfma_f32_16x16x32_bf16 v[130:133], v[164:167], v[198:201], v[130:133]
	v_mfma_f32_16x16x32_bf16 v[126:129], v[174:177], v[198:201], v[126:129]
	v_mfma_f32_16x16x32_bf16 v[126:129], v[168:171], v[194:197], v[126:129]
	v_mfma_f32_16x16x32_bf16 v[110:113], v[168:171], v[202:205], v[110:113]
	v_mfma_f32_16x16x32_bf16 v[110:113], v[174:177], v[206:209], v[110:113]
	v_mfma_f32_16x16x32_bf16 v[114:117], v[164:167], v[206:209], v[114:117]
	v_mfma_f32_16x16x32_bf16 v[114:117], v[160:163], v[202:205], v[114:117]
	v_mfma_f32_16x16x32_bf16 v[98:101], v[160:163], v[210:213], v[98:101]
	v_mfma_f32_16x16x32_bf16 v[98:101], v[164:167], v[214:217], v[98:101]
	v_mfma_f32_16x16x32_bf16 v[94:97], v[174:177], v[214:217], v[94:97]
	v_mfma_f32_16x16x32_bf16 v[94:97], v[168:171], v[210:213], v[94:97]
	v_mfma_f32_16x16x32_bf16 v[78:81], v[168:171], v[218:221], v[78:81]
	v_mfma_f32_16x16x32_bf16 v[78:81], v[174:177], v[222:225], v[78:81]
	v_mfma_f32_16x16x32_bf16 v[82:85], v[164:167], v[222:225], v[82:85]
	v_mfma_f32_16x16x32_bf16 v[82:85], v[160:163], v[218:221], v[82:85]
	s_setprio 0
	s_setprio 1
	v_mfma_f32_16x16x32_bf16 v[122:125], v[178:181], v[194:197], v[122:125]
	v_mfma_f32_16x16x32_bf16 v[122:125], v[182:185], v[198:201], v[122:125]
	v_mfma_f32_16x16x32_bf16 v[118:121], v[190:193], v[198:201], v[118:121]
	v_mfma_f32_16x16x32_bf16 v[118:121], v[186:189], v[194:197], v[118:121]
	v_mfma_f32_16x16x32_bf16 v[102:105], v[186:189], v[202:205], v[102:105]
	v_mfma_f32_16x16x32_bf16 v[102:105], v[190:193], v[206:209], v[102:105]
	v_mfma_f32_16x16x32_bf16 v[106:109], v[182:185], v[206:209], v[106:109]
	v_mfma_f32_16x16x32_bf16 v[106:109], v[178:181], v[202:205], v[106:109]
	v_mfma_f32_16x16x32_bf16 v[90:93], v[178:181], v[210:213], v[90:93]
	v_mfma_f32_16x16x32_bf16 v[90:93], v[182:185], v[214:217], v[90:93]
	v_mfma_f32_16x16x32_bf16 v[86:89], v[190:193], v[214:217], v[86:89]
	v_mfma_f32_16x16x32_bf16 v[86:89], v[186:189], v[210:213], v[86:89]
	v_mfma_f32_16x16x32_bf16 v[70:73], v[186:189], v[218:221], v[70:73]
	v_mfma_f32_16x16x32_bf16 v[70:73], v[190:193], v[222:225], v[70:73]
	v_mfma_f32_16x16x32_bf16 v[74:77], v[182:185], v[222:225], v[74:77]
	v_mfma_f32_16x16x32_bf16 v[74:77], v[178:181], v[218:221], v[74:77]
	s_setprio 0
	s_barrier
; #define PG8_STAGE(bufoff, gbase, voff) do { _Pragma("unroll") for (int _i = 0; _i < 2; ++_i) \
;         __builtin_amdgcn_global_load_lds((const unsigned*)((const char*)(gbase) + (voff)[_i]), (PG8_LAS unsigned*)(lds + (bufoff) + ldsw + _i * 8192), 16, 0, 0); } while (0)
; #define PG8_LDA(dst, b, h) do { _Pragma("unroll") for (int m = 0; m < 4; ++m) _Pragma("unroll") for (int k = 0; k < 2; ++k) dst[m][k] = *(const PG8_LAS bf16x8*)(lds + PG8_SA(b, h) + aoff + m * 2048 + k * 1024); } while (0)
; #define PG8_MMA(ai, bj, At, Bt) do { __builtin_amdgcn_s_setprio(1); _Pragma("unroll") for (int m = 0; m < 4; ++m) _Pragma("unroll") for (int n = 0; n < 2; ++n) _Pragma("unroll") for (int k = 0; k < 2; ++k) \
;         acc[ai][bj][m][n] = __builtin_amdgcn_mfma_f32_16x16x32_bf16(Bt[n][k], At[m][k], acc[ai][bj][m][n], 0, 0, 0); __builtin_amdgcn_s_setprio(0); } while (0)
; #define PG8_WAIT_V(n) asm volatile("s_waitcnt vmcnt(" #n ")" ::: "memory")
; #define PG8_WAIT_L(n) asm volatile("s_waitcnt lgkmcnt(" #n ")" ::: "memory")
; #define PG8_BAR __builtin_amdgcn_s_barrier()
; #define PG8_SCHED __builtin_amdgcn_sched_barrier(0)
; template <class Epi, class Sched, bool ALIGN_EPI>
; __device__ __forceinline__ void gemm_phase(PG8_LAS unsigned char* lds, const Gemm g, const Sched& S, const Epi& E) {
;     ...
;         for (int t = 0; t < nt; t += 2) {
;     ...
;             PG8_LDA(At, 1, 1); PG8_STAGE(PG8_SB(1, 0), b3, voffB); PG8_STAGE(PG8_SB(1, 1), b3 + hstepB, voffB); PG8_STAGE(PG8_SA(1, 0), a3, voffA);
;             PG8_WAIT_V(8); PG8_WAIT_L(0); PG8_BAR; PG8_MMA(1, 0, At, B0); PG8_MMA(1, 1, At, B1); PG8_BAR; PG8_SCHED;
	s_add_i32 s2, s2, s4
	v_lshl_add_u64 v[8:9], v[226:227], 0, s[16:17]
	s_mov_b32 m0, s2
	s_nop 0
	global_load_lds_dwordx4 v[8:9], off
	s_add_i32 m0, s2, 0x2000
	v_lshl_add_u64 v[8:9], v[228:229], 0, s[16:17]
	global_load_lds_dwordx4 v[8:9], off
	s_add_u32 s42, s42, 0x80080
	s_addc_u32 s43, s43, 0
	s_add_i32 s2, s63, s4
	v_lshl_add_u64 v[8:9], s[42:43], 0, v[136:137]
	s_mov_b32 m0, s2
	s_nop 0
	global_load_lds_dwordx4 v[8:9], off
	v_lshl_add_u64 v[8:9], s[42:43], 0, v[140:141]
	s_add_i32 m0, s2, 0x2000
	s_nop 0
	global_load_lds_dwordx4 v[8:9], off
	v_lshl_add_u64 v[8:9], v[230:231], 0, s[16:17]
	s_mov_b32 m0, s52
	s_nop 0
	global_load_lds_dwordx4 v[8:9], off
	v_lshl_add_u64 v[8:9], v[232:233], 0, s[16:17]
	s_mov_b32 m0, s53
	s_nop 0
	global_load_lds_dwordx4 v[8:9], off
	ds_read_b128 v[194:197], v159 offset:49152
	ds_read_b128 v[198:201], v159 offset:50176
	ds_read_b128 v[202:205], v159 offset:51200
	ds_read_b128 v[206:209], v159 offset:52224
	ds_read_b128 v[210:213], v159 offset:53248
	ds_read_b128 v[214:217], v159 offset:54272
	ds_read_b128 v[218:221], v159 offset:55296
	ds_read_b128 v[222:225], v159 offset:56320
	s_waitcnt vmcnt(8)
	s_waitcnt lgkmcnt(0)
	s_barrier
	s_setprio 1
	s_waitcnt lgkmcnt(0)
	v_mfma_f32_16x16x32_bf16 v[66:69], v[160:163], v[194:197], v[66:69]
	v_mfma_f32_16x16x32_bf16 v[66:69], v[164:167], v[198:201], v[66:69]
	v_mfma_f32_16x16x32_bf16 v[62:65], v[174:177], v[198:201], v[62:65]
	v_mfma_f32_16x16x32_bf16 v[62:65], v[168:171], v[194:197], v[62:65]
	v_mfma_f32_16x16x32_bf16 v[46:49], v[168:171], v[202:205], v[46:49]
	v_mfma_f32_16x16x32_bf16 v[46:49], v[174:177], v[206:209], v[46:49]
	v_mfma_f32_16x16x32_bf16 v[50:53], v[164:167], v[206:209], v[50:53]
	v_mfma_f32_16x16x32_bf16 v[50:53], v[160:163], v[202:205], v[50:53]
	v_mfma_f32_16x16x32_bf16 v[34:37], v[160:163], v[210:213], v[34:37]
	v_mfma_f32_16x16x32_bf16 v[34:37], v[164:167], v[214:217], v[34:37]
	v_mfma_f32_16x16x32_bf16 v[30:33], v[174:177], v[214:217], v[30:33]
	v_mfma_f32_16x16x32_bf16 v[30:33], v[168:171], v[210:213], v[30:33]
	v_mfma_f32_16x16x32_bf16 v[14:17], v[168:171], v[218:221], v[14:17]
	v_mfma_f32_16x16x32_bf16 v[14:17], v[174:177], v[222:225], v[14:17]
	v_mfma_f32_16x16x32_bf16 v[18:21], v[164:167], v[222:225], v[18:21]
	v_mfma_f32_16x16x32_bf16 v[18:21], v[160:163], v[218:221], v[18:21]
	s_setprio 0
	s_setprio 1
	v_mfma_f32_16x16x32_bf16 v[58:61], v[178:181], v[194:197], v[58:61]
	v_mfma_f32_16x16x32_bf16 v[54:57], v[186:189], v[194:197], v[54:57]
	v_mfma_f32_16x16x32_bf16 v[42:45], v[178:181], v[202:205], v[42:45]
	v_mfma_f32_16x16x32_bf16 v[38:41], v[186:189], v[202:205], v[38:41]
	v_mfma_f32_16x16x32_bf16 v[26:29], v[178:181], v[210:213], v[26:29]
	v_mfma_f32_16x16x32_bf16 v[22:25], v[186:189], v[210:213], v[22:25]
	v_mfma_f32_16x16x32_bf16 v[8:11], v[178:181], v[218:221], v[10:13]
	v_mfma_f32_16x16x32_bf16 v[4:7], v[186:189], v[218:221], v[4:7]
	v_mfma_f32_16x16x32_bf16 v[58:61], v[182:185], v[198:201], v[58:61]
	v_mfma_f32_16x16x32_bf16 v[54:57], v[190:193], v[198:201], v[54:57]
	v_mfma_f32_16x16x32_bf16 v[42:45], v[182:185], v[206:209], v[42:45]
	v_mfma_f32_16x16x32_bf16 v[38:41], v[190:193], v[206:209], v[38:41]
	v_mfma_f32_16x16x32_bf16 v[26:29], v[182:185], v[214:217], v[26:29]
	v_mfma_f32_16x16x32_bf16 v[22:25], v[190:193], v[214:217], v[22:25]
	v_mfma_f32_16x16x32_bf16 v[10:13], v[182:185], v[222:225], v[8:11]
	v_mfma_f32_16x16x32_bf16 v[6:9], v[190:193], v[222:225], v[4:7]
	s_setprio 0
	s_barrier
	s_add_i32 s62, s62, 2
	s_add_u32 s40, s40, 0x100
	s_addc_u32 s41, s41, 0
	s_cmp_gt_u32 s62, 29
	s_cbranch_scc1 .LBB0_842
